# P4: hardware v_sqrt_f32 for the scan input-normalisation factor (1 ulp) instead of the 16-instr correctly-rounded expansion; next-unit K/V tile prefetch in the P4 memory-attention loop
# speedup vs baseline: 1.0072x; 1.0072x over previous
.LBB0_549:
	s_cmp_lt_i32 s40, 5
	s_cselect_b64 s[4:5], -1, 0
	s_cmp_gt_i32 s41, 4
	s_cselect_b64 s[6:7], -1, 0
	s_and_b64 s[4:5], s[4:5], s[6:7]
	s_andn2_b64 vcc, exec, s[4:5]
	s_cbranch_vccnz .LBB0_569
	s_waitcnt lgkmcnt(0)
	s_cmpk_lt_i32 s33, 0xc1
	s_cselect_b64 s[4:5], -1, 0
	s_cmpk_lt_i32 s2, 0xc0
	s_cselect_b64 s[6:7], -1, 0
	v_mov_b32_e32 v213, v254
	s_or_b64 s[4:5], s[6:7], s[4:5]
	s_and_b64 vcc, exec, s[4:5]
	v_readfirstlane_b32 s22, v213
	s_cbranch_vccnz .LBB0_558
	s_waitcnt vmcnt(0)
	v_mov_b32_e32 v2, s0
	v_mov_b32_e32 v3, s1
	s_add_i32 s23, s2, 0xffffff40
	v_readfirstlane_b32 s4, v2
	v_readfirstlane_b32 s5, v3
	v_mov_b32_e32 v2, s0
	v_mov_b32_e32 v3, s1
	v_mov_b32_e32 v0, s0
	v_mov_b32_e32 v1, s1
	v_readfirstlane_b32 s6, v2
	v_readfirstlane_b32 s7, v3
	v_mov_b32_e32 v2, s0
	v_mov_b32_e32 v3, s1
	s_cmpk_gt_u32 s23, 0x1ff
	s_nop 0
	v_readfirstlane_b32 s12, v2
	v_readfirstlane_b32 s13, v3
	v_readfirstlane_b32 s14, v0
	v_readfirstlane_b32 s15, v1
	s_cbranch_scc1 .LBB0_558
	s_load_dwordx2 s[8:9], s[4:5], 0xc0
	s_load_dwordx2 s[10:11], s[6:7], 0xc0
	v_lshrrev_b32_e32 v2, 1, v254
	v_and_b32_e32 v154, 0x1e0, v2
	v_mov_b32_e32 v141, 0
	s_waitcnt lgkmcnt(0)
	s_add_u32 s4, s8, 0x1a000000
	s_addc_u32 s5, s9, 0
	s_lshl_b32 s3, s23, 6
	s_lshl_b32 s6, s23, 8
	s_and_b32 s3, s3, 0x7000
	s_and_b32 s6, s6, 0xf00
	s_or_b32 s3, s3, s6
	v_add_lshl_u32 v140, s3, v154, 9
	s_lshl_b32 s3, s23, 3
	v_and_b32_e32 v7, 31, v254
	s_mov_b32 s7, 0
	v_lshl_add_u64 v[0:1], s[4:5], 0, v[140:141]
	s_and_b32 s6, s3, 0x180
	v_lshl_add_u64 v[0:1], v[0:1], 0, s[6:7]
	v_lshlrev_b32_e32 v140, 9, v7
	v_lshl_add_u64 v[0:1], v[0:1], 0, v[140:141]
	v_and_b32_e32 v140, 16, v2
	v_lshl_add_u64 v[4:5], v[0:1], 0, v[140:141]
	global_load_dwordx4 v[0:3], v[4:5], off
	global_load_dwordx4 v[136:139], v[4:5], off offset:32
	global_load_dwordx4 v[132:135], v[4:5], off offset:64
	global_load_dwordx4 v[128:131], v[4:5], off offset:96
	v_mbcnt_lo_u32_b32 v12, -1, 0
	v_mbcnt_hi_u32_b32 v12, -1, v12
	v_and_b32_e32 v21, 64, v12
	v_xor_b32_e32 v13, 32, v12
	v_add_u32_e32 v21, 64, v21
	v_cmp_lt_i32_e32 vcc, v13, v21
	v_lshlrev_b32_e32 v6, 4, v254
	s_movk_i32 s6, 0x90
	v_cndmask_b32_e32 v12, v12, v13, vcc
	v_lshrrev_b32_e32 v140, 3, v254
	v_and_b32_e32 v9, 0x70, v6
	v_lshlrev_b32_e32 v155, 2, v12
	v_mul_lo_u32 v12, v140, s6
	v_add3_u32 v157, v12, v9, 0
	v_lshlrev_b64 v[12:13], 9, v[140:141]
	s_load_dwordx2 s[16:17], s[12:13], 0xc0
	s_load_dwordx2 s[8:9], s[14:15], 0xc0
	v_and_b32_e32 v5, 63, v254
	v_or_b32_e32 v12, v12, v9
	v_or_b32_e32 v8, 32, v5
	v_or_b32_e32 v6, 0x60, v5
	v_lshl_add_u64 v[12:13], s[10:11], 0, v[12:13]
	s_mov_b64 s[10:11], 0x3320c00
	v_lshrrev_b32_e32 v140, 5, v254
	v_lshlrev_b32_e32 v4, 8, v7
	v_bfe_u32 v10, v254, 5, 1
	v_mul_u32_u24_e32 v14, 0x90, v7
	v_mul_u32_u24_e32 v15, 0x90, v8
	v_mul_u32_u24_e32 v16, 0x90, v6
	v_or_b32_e32 v6, 0xa0, v5
	s_movk_i32 s12, 0x208
	v_mul_u32_u24_e32 v19, 0x208, v7
	v_mul_u32_u24_e32 v20, 0x208, v8
	v_lshlrev_b32_e32 v8, 10, v7
	v_lshlrev_b32_e32 v7, 4, v7
	v_lshl_add_u64 v[142:143], v[12:13], 0, s[10:11]
	v_lshlrev_b64 v[12:13], 9, v[140:141]
	v_lshl_add_u32 v11, v10, 4, 0
	v_mul_u32_u24_e32 v17, 0x90, v6
	v_or_b32_e32 v5, 0xe0, v5
	v_lshlrev_b32_e32 v6, 3, v10
	v_mul_lo_u32 v9, v140, s12
	v_or_b32_e32 v12, v12, v7
	v_mul_u32_u24_e32 v5, 0x90, v5
	v_sub_u32_e32 v18, v11, v6
	v_lshlrev_b32_e32 v10, 2, v10
	s_lshl_b32 s6, s2, 2
	s_lshl_b32 s25, s33, 2
	v_add3_u32 v9, v9, v7, 0
	s_waitcnt lgkmcnt(0)
	v_lshl_add_u64 v[12:13], s[16:17], 0, v[12:13]
	s_mov_b64 s[10:11], 0x3520c00
	s_add_i32 s3, s33, 0xffffff40
	v_add_u32_e32 v156, 0xfffffe00, v254
	s_add_i32 s24, s6, 0xfffffd00
	s_addk_i32 s25, 0xfd00
	v_add_u32_e32 v158, 0x9000, v9
	v_lshl_add_u64 v[144:145], v[12:13], 0, s[10:11]
	s_mov_b64 s[10:11], 0x8000
	s_movk_i32 s26, 0x5ff
	s_mov_b64 s[12:13], 0x2000
	v_add_u32_e32 v159, v11, v14
	v_add_u32_e32 v160, v11, v15
	v_add_u32_e32 v161, v11, v16
	v_add_u32_e32 v162, v11, v17
	v_add_u32_e32 v163, v11, v5
	s_mov_b32 s27, 0xff800000
	v_add_u32_e32 v164, v18, v19
	v_add_u32_e32 v165, v18, v20
	v_lshlrev_b32_e32 v146, 1, v4
	v_lshlrev_b32_e32 v148, 1, v6
	v_lshlrev_b32_e32 v150, 1, v8
	v_lshlrev_b32_e32 v152, 1, v10
	s_mov_b64 s[14:15], 0x1b000600
	s_mov_b32 s28, 0x1b000000
	v_add_u32_e32 v248, 0x2080, v158
	v_add_u32_e32 v249, 0x4100, v158
	v_add_u32_e32 v250, 0x6180, v158
	s_mov_b32 s98, s23
	s_bfe_u32 s100, s98, 0x20004
	s_lshr_b32 s98, s98, 6
	s_lshl_b32 s98, s98, 17
	s_lshl_b32 s99, s100, 7
	s_lshl_b32 s100, s100, 15
	s_add_u32 s100, s100, s98
	s_or_b32 s98, s98, s99
	s_mov_b32 s99, 0
	s_mov_b32 s101, 0
	v_lshl_add_u64 v[214:215], v[142:143], 0, s[98:99]
	global_load_dwordx4 v[216:219], v[214:215], off
	v_lshl_add_u64 v[214:215], v[214:215], 0, s[10:11]
	global_load_dwordx4 v[220:223], v[214:215], off
	v_lshl_add_u64 v[214:215], v[214:215], 0, s[10:11]
	global_load_dwordx4 v[224:227], v[214:215], off
	v_lshl_add_u64 v[214:215], v[214:215], 0, s[10:11]
	global_load_dwordx4 v[228:231], v[214:215], off
	v_lshl_add_u64 v[214:215], v[144:145], 0, s[100:101]
	global_load_dwordx4 v[232:235], v[214:215], off
	v_lshl_add_u64 v[214:215], v[214:215], 0, s[12:13]
	global_load_dwordx4 v[236:239], v[214:215], off
	v_lshl_add_u64 v[214:215], v[214:215], 0, s[12:13]
	global_load_dwordx4 v[240:243], v[214:215], off
	v_lshl_add_u64 v[214:215], v[214:215], 0, s[12:13]
	global_load_dwordx4 v[244:247], v[214:215], off
	s_waitcnt vmcnt(0)
	s_branch .Lp4m_write

.Lp4m_write:
	s_ashr_i32 s18, s23, 6
	s_ashr_i32 s19, s18, 31
	ds_write_b128 v157, v[216:219]
	ds_write_b128 v157, v[220:223] offset:9216
	ds_write_b128 v157, v[224:227] offset:18432
	ds_write_b128 v157, v[228:231] offset:27648
	ds_write2_b64 v158, v[232:233], v[234:235] offset1:1
	ds_write2_b64 v248, v[236:237], v[238:239] offset1:1
	ds_write2_b64 v249, v[240:241], v[242:243] offset1:1
	ds_write2_b64 v250, v[244:245], v[246:247] offset1:1
	s_waitcnt lgkmcnt(0)
	s_barrier
	s_add_i32 s98, s3, s23
	s_cmpk_lt_i32 s98, 0x200
	s_cbranch_scc0 .Lp4m_nopf
	s_bfe_u32 s100, s98, 0x20004
	s_lshr_b32 s98, s98, 6
	s_lshl_b32 s98, s98, 17
	s_lshl_b32 s99, s100, 7
	s_lshl_b32 s100, s100, 15
	s_add_u32 s100, s100, s98
	s_or_b32 s98, s98, s99
	s_mov_b32 s99, 0
	s_mov_b32 s101, 0
	v_lshl_add_u64 v[214:215], v[142:143], 0, s[98:99]
	global_load_dwordx4 v[216:219], v[214:215], off
	v_lshl_add_u64 v[214:215], v[214:215], 0, s[10:11]
	global_load_dwordx4 v[220:223], v[214:215], off
	v_lshl_add_u64 v[214:215], v[214:215], 0, s[10:11]
	global_load_dwordx4 v[224:227], v[214:215], off
	v_lshl_add_u64 v[214:215], v[214:215], 0, s[10:11]
	global_load_dwordx4 v[228:231], v[214:215], off
	v_lshl_add_u64 v[214:215], v[144:145], 0, s[100:101]
	global_load_dwordx4 v[232:235], v[214:215], off
	v_lshl_add_u64 v[214:215], v[214:215], 0, s[12:13]
	global_load_dwordx4 v[236:239], v[214:215], off
	v_lshl_add_u64 v[214:215], v[214:215], 0, s[12:13]
	global_load_dwordx4 v[240:243], v[214:215], off
	v_lshl_add_u64 v[214:215], v[214:215], 0, s[12:13]
	global_load_dwordx4 v[244:247], v[214:215], off
.Lp4m_nopf:
	ds_read_b128 v[4:7], v159
	ds_read_b128 v[8:11], v159 offset:32
	s_waitcnt lgkmcnt(1)
	v_mfma_f32_32x32x16_bf16 v[112:127], v[4:7], v[0:3], 0
	s_lshl_b32 s6, s23, 8
	s_and_b32 s21, s6, 0xf00
	s_add_i32 s20, s3, s23
	s_cmpk_lt_i32 s20, 0x200
	s_cselect_b64 s[16:17], -1, 0
	s_and_b64 s[30:31], s[16:17], exec
	s_cselect_b32 s6, s20, s23
	s_waitcnt lgkmcnt(0)
	v_mfma_f32_32x32x16_bf16 v[112:127], v[8:11], v[136:139], v[112:127]
	ds_read_b128 v[4:7], v159 offset:64
	ds_read_b128 v[8:11], v159 offset:96
	s_ashr_i32 s30, s6, 6
	s_ashr_i32 s31, s30, 31
	s_lshl_b32 s29, s6, 8
	s_and_b32 s29, s29, 0xf00
	s_lshl_b64 s[30:31], s[30:31], 21
	s_add_u32 s30, s4, s30
	s_waitcnt lgkmcnt(1)
	v_mfma_f32_32x32x16_bf16 v[112:127], v[4:7], v[132:135], v[112:127]
	s_addc_u32 s31, s5, s31
	v_add_lshl_u32 v140, s29, v154, 9
	v_lshl_add_u64 v[190:191], s[30:31], 0, v[140:141]
	s_lshl_b32 s6, s6, 3
	s_and_b32 s6, s6, 0x180
	s_lshl_b64 s[18:19], s[18:19], 23
	s_add_u32 s18, s8, s18
	s_waitcnt lgkmcnt(0)
	v_mfma_f32_32x32x16_bf16 v[112:127], v[8:11], v[128:131], v[112:127]
	ds_read_b128 v[4:7], v160
	ds_read_b128 v[8:11], v160 offset:32
	s_addc_u32 s19, s9, s19
	s_add_i32 s24, s24, s25
	s_waitcnt lgkmcnt(1)
	v_mfma_f32_32x32x16_bf16 v[96:111], v[4:7], v[0:3], 0
	s_waitcnt lgkmcnt(0)
	v_mfma_f32_32x32x16_bf16 v[96:111], v[8:11], v[136:139], v[96:111]
	ds_read_b128 v[4:7], v160 offset:64
	ds_read_b128 v[8:11], v160 offset:96
	s_waitcnt lgkmcnt(1)
	v_mfma_f32_32x32x16_bf16 v[96:111], v[4:7], v[132:135], v[96:111]
	s_waitcnt lgkmcnt(0)
	v_mfma_f32_32x32x16_bf16 v[96:111], v[8:11], v[128:131], v[96:111]
	ds_read_b128 v[4:7], v159 offset:9216
	ds_read_b128 v[8:11], v159 offset:9248
	s_waitcnt lgkmcnt(1)
	v_mfma_f32_32x32x16_bf16 v[80:95], v[4:7], v[0:3], 0
	s_waitcnt lgkmcnt(0)
	v_mfma_f32_32x32x16_bf16 v[80:95], v[8:11], v[136:139], v[80:95]
	ds_read_b128 v[4:7], v159 offset:9280
	ds_read_b128 v[8:11], v159 offset:9312
	s_waitcnt lgkmcnt(1)
	v_mfma_f32_32x32x16_bf16 v[80:95], v[4:7], v[132:135], v[80:95]
	s_waitcnt lgkmcnt(0)
	v_mfma_f32_32x32x16_bf16 v[80:95], v[8:11], v[128:131], v[80:95]
	ds_read_b128 v[4:7], v161
	ds_read_b128 v[8:11], v161 offset:32
	s_waitcnt lgkmcnt(1)
	v_mfma_f32_32x32x16_bf16 v[64:79], v[4:7], v[0:3], 0
	s_waitcnt lgkmcnt(0)
	v_mfma_f32_32x32x16_bf16 v[64:79], v[8:11], v[136:139], v[64:79]
	ds_read_b128 v[4:7], v161 offset:64
	ds_read_b128 v[8:11], v161 offset:96
	s_waitcnt lgkmcnt(1)
	v_mfma_f32_32x32x16_bf16 v[64:79], v[4:7], v[132:135], v[64:79]
	s_waitcnt lgkmcnt(0)
	v_mfma_f32_32x32x16_bf16 v[64:79], v[8:11], v[128:131], v[64:79]
	ds_read_b128 v[4:7], v159 offset:18432
	ds_read_b128 v[8:11], v159 offset:18464
	s_waitcnt lgkmcnt(1)
	v_mfma_f32_32x32x16_bf16 v[48:63], v[4:7], v[0:3], 0
	s_waitcnt lgkmcnt(0)
	v_mfma_f32_32x32x16_bf16 v[48:63], v[8:11], v[136:139], v[48:63]
	ds_read_b128 v[4:7], v159 offset:18496
	ds_read_b128 v[8:11], v159 offset:18528
	s_waitcnt lgkmcnt(1)
	v_mfma_f32_32x32x16_bf16 v[48:63], v[4:7], v[132:135], v[48:63]
	ds_read_b128 v[4:7], v162
	s_waitcnt lgkmcnt(1)
	v_mfma_f32_32x32x16_bf16 v[48:63], v[8:11], v[128:131], v[48:63]
	ds_read_b128 v[8:11], v162 offset:32
	s_waitcnt lgkmcnt(1)
	v_mfma_f32_32x32x16_bf16 v[32:47], v[4:7], v[0:3], 0
	ds_read_b128 v[4:7], v162 offset:64
	s_waitcnt lgkmcnt(1)
	v_mfma_f32_32x32x16_bf16 v[32:47], v[8:11], v[136:139], v[32:47]
	ds_read_b128 v[8:11], v162 offset:96
	s_waitcnt lgkmcnt(1)
	v_mfma_f32_32x32x16_bf16 v[32:47], v[4:7], v[132:135], v[32:47]
	ds_read_b128 v[4:7], v159 offset:27648
	ds_read_b128 v[12:15], v159 offset:27680
	ds_read_b128 v[166:169], v159 offset:27712
	ds_read_b128 v[170:173], v159 offset:27744
	ds_read_b128 v[174:177], v163
	ds_read_b128 v[178:181], v163 offset:32
	ds_read_b128 v[182:185], v163 offset:64
	ds_read_b128 v[186:189], v163 offset:96
	s_waitcnt lgkmcnt(8)
	v_mfma_f32_32x32x16_bf16 v[32:47], v[8:11], v[128:131], v[32:47]
	v_max3_f32 v8, v112, s27, v113
	v_max3_f32 v8, v8, v114, v115
	v_max3_f32 v8, v8, v116, v117
	v_max3_f32 v8, v8, v118, v119
	v_max3_f32 v8, v8, v120, v121
	v_max3_f32 v8, v8, v122, v123
	v_max3_f32 v8, v8, v124, v125
	s_waitcnt lgkmcnt(7)
	v_mfma_f32_32x32x16_bf16 v[16:31], v[4:7], v[0:3], 0
	v_max3_f32 v4, v8, v126, v127
	v_max3_f32 v4, v4, v96, v97
	v_max3_f32 v4, v4, v98, v99
	v_max3_f32 v4, v4, v100, v101
	v_max3_f32 v4, v4, v102, v103
	v_max3_f32 v4, v4, v104, v105
	v_max3_f32 v4, v4, v106, v107
	v_max3_f32 v4, v4, v108, v109
	v_max3_f32 v4, v4, v110, v111
	v_max3_f32 v4, v4, v80, v81
	v_max3_f32 v4, v4, v82, v83
	v_max3_f32 v4, v4, v84, v85
	v_max3_f32 v4, v4, v86, v87
	v_max3_f32 v4, v4, v88, v89
	v_max3_f32 v4, v4, v90, v91
	v_max3_f32 v4, v4, v92, v93
	v_max3_f32 v4, v4, v94, v95
	v_max3_f32 v4, v4, v64, v65
	v_max3_f32 v4, v4, v66, v67
	v_max3_f32 v4, v4, v68, v69
	v_max3_f32 v4, v4, v70, v71
	v_max3_f32 v4, v4, v72, v73
	v_max3_f32 v4, v4, v74, v75
	v_max3_f32 v4, v4, v76, v77
	v_max3_f32 v4, v4, v78, v79
	v_max3_f32 v4, v4, v48, v49
	v_max3_f32 v4, v4, v50, v51
	s_waitcnt lgkmcnt(6)
	v_mfma_f32_32x32x16_bf16 v[16:31], v[12:15], v[136:139], v[16:31]
	v_max3_f32 v140, v4, v52, v53
	v_max3_f32 v140, v140, v54, v55
	v_max3_f32 v140, v140, v56, v57
	v_max3_f32 v140, v140, v58, v59
	v_max3_f32 v140, v140, v60, v61
	v_max3_f32 v140, v140, v62, v63
	v_max3_f32 v140, v140, v32, v33
	s_waitcnt lgkmcnt(3)
	v_mfma_f32_32x32x16_bf16 v[0:15], v[174:177], v[0:3], 0
	v_max3_f32 v140, v140, v34, v35
	v_mfma_f32_32x32x16_bf16 v[16:31], v[166:169], v[132:135], v[16:31]
	s_waitcnt lgkmcnt(2)
	v_mfma_f32_32x32x16_bf16 v[0:15], v[178:181], v[136:139], v[0:15]
	v_max3_f32 v136, v140, v36, v37
	v_max3_f32 v136, v136, v38, v39
	v_max3_f32 v136, v136, v40, v41
	v_max3_f32 v136, v136, v42, v43
	v_max3_f32 v136, v136, v44, v45
	v_max3_f32 v136, v136, v46, v47
	v_add_lshl_u32 v140, s21, v154, 11
	v_mfma_f32_32x32x16_bf16 v[16:31], v[170:173], v[128:131], v[16:31]
	s_waitcnt lgkmcnt(1)
	v_mfma_f32_32x32x16_bf16 v[0:15], v[182:185], v[132:135], v[0:15]
	s_nop 9
	v_max3_f32 v136, v136, v16, v17
	v_max3_f32 v132, v136, v18, v19
	v_max3_f32 v132, v132, v20, v21
	v_max3_f32 v132, v132, v22, v23
	v_max3_f32 v132, v132, v24, v25
	v_max3_f32 v132, v132, v26, v27
	v_max3_f32 v132, v132, v28, v29
	s_waitcnt lgkmcnt(0)
	v_mfma_f32_32x32x16_bf16 v[0:15], v[186:189], v[128:131], v[0:15]
	v_max3_f32 v132, v132, v30, v31
	s_nop 10
	v_max3_f32 v128, v132, v0, v1
	v_max3_f32 v128, v128, v2, v3
	v_max3_f32 v128, v128, v4, v5
	v_max3_f32 v128, v128, v6, v7
	v_max3_f32 v128, v128, v8, v9
	v_max3_f32 v128, v128, v10, v11
	v_max3_f32 v128, v128, v12, v13
	v_max3_f32 v130, v128, v14, v15
	ds_bpermute_b32 v131, v155, v130
	v_lshl_add_u64 v[128:129], v[190:191], 0, s[6:7]
	s_lshl_b32 s6, s23, 3
	s_and_b32 s6, s6, 0x180
	s_mov_b32 s23, s20
	s_waitcnt lgkmcnt(0)
	v_max_f32_e32 v131, v131, v131
	v_max_f32_e32 v130, v130, v131
	v_sub_f32_e32 v112, v112, v130
	v_exp_f32_e32 v112, v112
	v_sub_f32_e32 v113, v113, v130
	v_exp_f32_e32 v113, v113
	v_sub_f32_e32 v114, v114, v130
	v_exp_f32_e32 v114, v114
	v_sub_f32_e32 v115, v115, v130
	v_exp_f32_e32 v115, v115
	v_sub_f32_e32 v116, v116, v130
	v_add_f32_e32 v131, 0, v112
	v_exp_f32_e32 v116, v116
	v_sub_f32_e32 v117, v117, v130
	v_add_f32_e32 v131, v113, v131
	v_exp_f32_e32 v117, v117
	v_sub_f32_e32 v118, v118, v130
	v_add_f32_e32 v131, v114, v131
	v_exp_f32_e32 v118, v118
	v_sub_f32_e32 v119, v119, v130
	v_add_f32_e32 v131, v115, v131
	v_exp_f32_e32 v119, v119
	v_sub_f32_e32 v120, v120, v130
	v_add_f32_e32 v131, v116, v131
	v_exp_f32_e32 v120, v120
	v_sub_f32_e32 v121, v121, v130
	v_add_f32_e32 v131, v117, v131
	v_exp_f32_e32 v121, v121
	v_sub_f32_e32 v122, v122, v130
	v_add_f32_e32 v131, v118, v131
	v_exp_f32_e32 v122, v122
	v_sub_f32_e32 v123, v123, v130
	v_add_f32_e32 v131, v119, v131
	v_exp_f32_e32 v123, v123
	v_sub_f32_e32 v124, v124, v130
	v_add_f32_e32 v131, v120, v131
	v_exp_f32_e32 v124, v124
	v_sub_f32_e32 v125, v125, v130
	v_add_f32_e32 v131, v121, v131
	v_exp_f32_e32 v125, v125
	v_sub_f32_e32 v126, v126, v130
	v_add_f32_e32 v131, v122, v131
	v_exp_f32_e32 v126, v126
	v_sub_f32_e32 v127, v127, v130
	v_add_f32_e32 v131, v123, v131
	v_exp_f32_e32 v127, v127
	v_sub_f32_e32 v96, v96, v130
	v_add_f32_e32 v131, v124, v131
	v_exp_f32_e32 v96, v96
	v_sub_f32_e32 v97, v97, v130
	v_add_f32_e32 v131, v125, v131
	v_exp_f32_e32 v97, v97
	v_sub_f32_e32 v98, v98, v130
	v_add_f32_e32 v131, v126, v131
	v_exp_f32_e32 v98, v98
	v_sub_f32_e32 v99, v99, v130
	v_add_f32_e32 v131, v127, v131
	v_exp_f32_e32 v99, v99
	v_sub_f32_e32 v100, v100, v130
	v_add_f32_e32 v131, v96, v131
	v_exp_f32_e32 v100, v100
	v_sub_f32_e32 v101, v101, v130
	v_add_f32_e32 v131, v97, v131
	v_exp_f32_e32 v101, v101
	v_sub_f32_e32 v102, v102, v130
	v_add_f32_e32 v131, v98, v131
	v_exp_f32_e32 v102, v102
	v_sub_f32_e32 v103, v103, v130
	v_add_f32_e32 v131, v99, v131
	v_exp_f32_e32 v103, v103
	v_sub_f32_e32 v104, v104, v130
	v_add_f32_e32 v131, v100, v131
	v_exp_f32_e32 v104, v104
	v_sub_f32_e32 v105, v105, v130
	v_add_f32_e32 v131, v101, v131
	v_exp_f32_e32 v105, v105
	v_sub_f32_e32 v106, v106, v130
	v_add_f32_e32 v131, v102, v131
	v_exp_f32_e32 v106, v106
	v_sub_f32_e32 v107, v107, v130
	v_add_f32_e32 v131, v103, v131
	v_exp_f32_e32 v107, v107
	v_sub_f32_e32 v108, v108, v130
	v_add_f32_e32 v131, v104, v131
	v_exp_f32_e32 v108, v108
	v_sub_f32_e32 v109, v109, v130
	v_add_f32_e32 v131, v105, v131
	v_exp_f32_e32 v109, v109
	v_sub_f32_e32 v110, v110, v130
	v_add_f32_e32 v131, v106, v131
	v_exp_f32_e32 v110, v110
	v_sub_f32_e32 v111, v111, v130
	v_add_f32_e32 v131, v107, v131
	v_exp_f32_e32 v111, v111
	v_sub_f32_e32 v80, v80, v130
	v_add_f32_e32 v131, v108, v131
	v_exp_f32_e32 v132, v80
	v_sub_f32_e32 v80, v81, v130
	v_add_f32_e32 v131, v109, v131
	v_exp_f32_e32 v133, v80
	v_sub_f32_e32 v80, v82, v130
	v_add_f32_e32 v131, v110, v131
	v_exp_f32_e32 v134, v80
	v_sub_f32_e32 v81, v83, v130
	v_add_f32_e32 v80, v111, v131
	v_exp_f32_e32 v131, v81
	v_sub_f32_e32 v81, v84, v130
	v_add_f32_e32 v80, v132, v80
	v_exp_f32_e32 v135, v81
	v_sub_f32_e32 v81, v85, v130
	v_add_f32_e32 v80, v133, v80
	v_exp_f32_e32 v136, v81
	v_sub_f32_e32 v81, v86, v130
	v_add_f32_e32 v80, v134, v80
	v_exp_f32_e32 v137, v81
	v_sub_f32_e32 v81, v87, v130
	v_add_f32_e32 v80, v131, v80
	v_exp_f32_e32 v138, v81
	v_sub_f32_e32 v81, v88, v130
	v_add_f32_e32 v80, v135, v80
	v_exp_f32_e32 v88, v81
	v_sub_f32_e32 v81, v89, v130
	v_add_f32_e32 v80, v136, v80
	v_exp_f32_e32 v89, v81
	v_sub_f32_e32 v81, v90, v130
	v_add_f32_e32 v80, v137, v80
	v_exp_f32_e32 v90, v81
	v_sub_f32_e32 v81, v91, v130
	v_add_f32_e32 v80, v138, v80
	v_exp_f32_e32 v91, v81
	v_sub_f32_e32 v81, v92, v130
	v_add_f32_e32 v80, v88, v80
	v_exp_f32_e32 v92, v81
	v_sub_f32_e32 v81, v93, v130
	v_add_f32_e32 v80, v89, v80
	v_exp_f32_e32 v93, v81
	v_sub_f32_e32 v81, v94, v130
	v_add_f32_e32 v80, v90, v80
	v_exp_f32_e32 v94, v81
	v_sub_f32_e32 v81, v95, v130
	v_add_f32_e32 v80, v91, v80
	v_exp_f32_e32 v95, v81
	v_sub_f32_e32 v64, v64, v130
	v_add_f32_e32 v80, v92, v80
	v_exp_f32_e32 v139, v64
	v_sub_f32_e32 v64, v65, v130
	v_add_f32_e32 v80, v93, v80
	v_exp_f32_e32 v147, v64
	v_sub_f32_e32 v64, v66, v130
	v_add_f32_e32 v80, v94, v80
	v_exp_f32_e32 v149, v64
	v_sub_f32_e32 v65, v67, v130
	v_add_f32_e32 v64, v95, v80
	v_exp_f32_e32 v151, v65
	v_sub_f32_e32 v65, v68, v130
	v_add_f32_e32 v64, v139, v64
	v_exp_f32_e32 v153, v65
	v_sub_f32_e32 v65, v69, v130
	v_add_f32_e32 v64, v147, v64
	v_exp_f32_e32 v166, v65
	v_sub_f32_e32 v65, v70, v130
	v_add_f32_e32 v64, v149, v64
	v_exp_f32_e32 v167, v65
	v_sub_f32_e32 v65, v71, v130
	v_add_f32_e32 v64, v151, v64
	v_exp_f32_e32 v168, v65
	v_sub_f32_e32 v65, v72, v130
	v_add_f32_e32 v64, v153, v64
	v_exp_f32_e32 v169, v65
	v_sub_f32_e32 v65, v73, v130
	v_add_f32_e32 v64, v166, v64
	v_exp_f32_e32 v170, v65
	v_sub_f32_e32 v65, v74, v130
	v_add_f32_e32 v64, v167, v64
	v_exp_f32_e32 v171, v65
	v_sub_f32_e32 v65, v75, v130
	v_add_f32_e32 v64, v168, v64
	v_exp_f32_e32 v172, v65
	v_sub_f32_e32 v65, v76, v130
	v_add_f32_e32 v64, v169, v64
	v_exp_f32_e32 v173, v65
	v_sub_f32_e32 v65, v77, v130
	v_add_f32_e32 v64, v170, v64
	v_exp_f32_e32 v174, v65
	v_sub_f32_e32 v65, v78, v130
	v_add_f32_e32 v64, v171, v64
	v_exp_f32_e32 v175, v65
	v_sub_f32_e32 v65, v79, v130
	v_add_f32_e32 v64, v172, v64
	v_exp_f32_e32 v176, v65
	v_sub_f32_e32 v48, v48, v130
	v_add_f32_e32 v64, v173, v64
	v_exp_f32_e32 v177, v48
	v_sub_f32_e32 v48, v49, v130
	v_add_f32_e32 v64, v174, v64
	v_exp_f32_e32 v178, v48
	v_sub_f32_e32 v48, v50, v130
	v_add_f32_e32 v64, v175, v64
	v_exp_f32_e32 v179, v48
	v_sub_f32_e32 v49, v51, v130
	v_add_f32_e32 v48, v176, v64
	v_exp_f32_e32 v180, v49
	v_sub_f32_e32 v49, v52, v130
	v_add_f32_e32 v48, v177, v48
	v_exp_f32_e32 v181, v49
	v_sub_f32_e32 v49, v53, v130
	v_add_f32_e32 v48, v178, v48
	v_exp_f32_e32 v182, v49
	v_sub_f32_e32 v49, v54, v130
	v_add_f32_e32 v48, v179, v48
	v_exp_f32_e32 v183, v49
	v_sub_f32_e32 v49, v55, v130
	v_add_f32_e32 v48, v180, v48
	v_exp_f32_e32 v184, v49
	v_sub_f32_e32 v49, v56, v130
	v_add_f32_e32 v48, v181, v48
	v_exp_f32_e32 v185, v49
	v_sub_f32_e32 v49, v57, v130
	v_add_f32_e32 v48, v182, v48
	v_exp_f32_e32 v186, v49
	v_sub_f32_e32 v49, v58, v130
	v_add_f32_e32 v48, v183, v48
	v_exp_f32_e32 v187, v49
	v_sub_f32_e32 v49, v59, v130
	v_add_f32_e32 v48, v184, v48
	v_exp_f32_e32 v188, v49
	v_sub_f32_e32 v49, v60, v130
	v_add_f32_e32 v48, v185, v48
	v_exp_f32_e32 v189, v49
	v_sub_f32_e32 v49, v61, v130
	v_add_f32_e32 v48, v186, v48
	v_exp_f32_e32 v190, v49
	v_sub_f32_e32 v49, v62, v130
	v_add_f32_e32 v48, v187, v48
	v_exp_f32_e32 v191, v49
	v_sub_f32_e32 v49, v63, v130
	v_add_f32_e32 v48, v188, v48
	v_exp_f32_e32 v192, v49
	v_sub_f32_e32 v32, v32, v130
	v_add_f32_e32 v48, v189, v48
	v_exp_f32_e32 v193, v32
	v_sub_f32_e32 v32, v33, v130
	v_add_f32_e32 v48, v190, v48
	v_exp_f32_e32 v194, v32
	v_sub_f32_e32 v32, v34, v130
	v_add_f32_e32 v48, v191, v48
	v_exp_f32_e32 v195, v32
	v_sub_f32_e32 v33, v35, v130
	v_add_f32_e32 v32, v192, v48
	v_exp_f32_e32 v196, v33
	v_sub_f32_e32 v33, v36, v130
	v_add_f32_e32 v32, v193, v32
	v_exp_f32_e32 v197, v33
	v_sub_f32_e32 v33, v37, v130
	v_add_f32_e32 v32, v194, v32
	v_exp_f32_e32 v198, v33
	v_sub_f32_e32 v33, v38, v130
	v_add_f32_e32 v32, v195, v32
	v_exp_f32_e32 v199, v33
	v_add_f32_e32 v32, v196, v32
	v_add_f32_e32 v32, v197, v32
	v_add_f32_e32 v32, v198, v32
	v_add_f32_e32 v38, v199, v32
	v_sub_f32_e32 v32, v39, v130
	v_cvt_pk_bf16_f32 v34, v112, v113
	v_add_u32_e32 v33, 0x9000, v164
	v_exp_f32_e32 v112, v32
	v_add_u32_e32 v32, 0x9000, v165
	v_cvt_pk_bf16_f32 v35, v114, v115
	v_cvt_pk_bf16_f32 v36, v116, v117
	v_cvt_pk_bf16_f32 v37, v118, v119
	ds_read2_b64 v[48:51], v33 offset1:2
	ds_read2_b64 v[52:55], v32 offset1:2
	v_sub_f32_e32 v39, v40, v130
	v_exp_f32_e32 v113, v39
	s_waitcnt lgkmcnt(1)
	v_mfma_f32_32x32x16_bf16 v[64:79], v[48:51], v[34:37], 0
	v_cvt_pk_bf16_f32 v80, v120, v121
	v_cvt_pk_bf16_f32 v81, v122, v123
	v_cvt_pk_bf16_f32 v82, v124, v125
	v_cvt_pk_bf16_f32 v83, v126, v127
	ds_read2_b64 v[84:87], v33 offset0:4 offset1:6
	v_sub_f32_e32 v16, v16, v130
	v_sub_f32_e32 v17, v17, v130
	s_waitcnt lgkmcnt(1)
	v_mfma_f32_32x32x16_bf16 v[48:63], v[52:55], v[34:37], 0
	v_add_f32_e32 v34, v112, v38
	v_add_f32_e32 v38, v113, v34
	v_sub_f32_e32 v34, v41, v130
	v_exp_f32_e32 v114, v34
	v_sub_f32_e32 v34, v42, v130
	v_exp_f32_e32 v115, v34
	ds_read2_b64 v[34:37], v32 offset0:4 offset1:6
	v_add_f32_e32 v38, v114, v38
	s_waitcnt lgkmcnt(0)
	v_mfma_f32_32x32x16_bf16 v[48:63], v[34:37], v[80:83], v[48:63]
	v_sub_f32_e32 v34, v43, v130
	v_add_f32_e32 v116, v115, v38
	v_cvt_pk_bf16_f32 v38, v96, v97
	v_exp_f32_e32 v96, v34
	v_sub_f32_e32 v34, v44, v130
	v_exp_f32_e32 v97, v34
	v_sub_f32_e32 v34, v45, v130
	v_cvt_pk_bf16_f32 v39, v98, v99
	v_cvt_pk_bf16_f32 v40, v100, v101
	v_cvt_pk_bf16_f32 v41, v102, v103
	v_exp_f32_e32 v98, v34
	ds_read2_b64 v[34:37], v32 offset0:8 offset1:10
	v_mfma_f32_32x32x16_bf16 v[64:79], v[84:87], v[80:83], v[64:79]
	ds_read2_b64 v[84:87], v33 offset0:8 offset1:10
	v_sub_f32_e32 v42, v46, v130
	v_exp_f32_e32 v46, v42
	v_cvt_pk_bf16_f32 v42, v104, v105
	v_cvt_pk_bf16_f32 v43, v106, v107
	v_cvt_pk_bf16_f32 v44, v108, v109
	v_cvt_pk_bf16_f32 v45, v110, v111
	s_waitcnt lgkmcnt(1)
	v_mfma_f32_32x32x16_bf16 v[48:63], v[34:37], v[38:41], v[48:63]
	v_add_f32_e32 v34, v96, v116
	v_add_f32_e32 v34, v97, v34
	ds_read2_b64 v[80:83], v33 offset0:12 offset1:14
	v_add_f32_e32 v34, v98, v34
	v_sub_f32_e32 v0, v0, v130
	v_sub_f32_e32 v1, v1, v130
	s_waitcnt lgkmcnt(1)
	v_mfma_f32_32x32x16_bf16 v[64:79], v[84:87], v[38:41], v[64:79]
	v_add_f32_e32 v84, v46, v34
	v_sub_f32_e32 v34, v47, v130
	v_exp_f32_e32 v47, v34
	ds_read2_b64 v[34:37], v32 offset0:12 offset1:14
	v_cvt_pk_bf16_f32 v38, v132, v133
	v_cvt_pk_bf16_f32 v39, v134, v131
	v_cvt_pk_bf16_f32 v40, v135, v136
	s_waitcnt lgkmcnt(1)
	v_mfma_f32_32x32x16_bf16 v[64:79], v[80:83], v[42:45], v[64:79]
	v_cvt_pk_bf16_f32 v41, v137, v138
	ds_read2_b64 v[80:83], v33 offset0:16 offset1:18
	v_exp_f32_e32 v85, v16
	v_add_f32_e32 v16, v47, v84
	v_exp_f32_e32 v84, v17
	v_sub_f32_e32 v17, v18, v130
	v_exp_f32_e32 v86, v17
	s_waitcnt lgkmcnt(1)
	v_mfma_f32_32x32x16_bf16 v[48:63], v[34:37], v[42:45], v[48:63]
	ds_read2_b64 v[34:37], v32 offset0:16 offset1:18
	v_add_f32_e32 v16, v85, v16
	v_add_f32_e32 v16, v84, v16
	v_add_f32_e32 v87, v86, v16
	v_sub_f32_e32 v16, v19, v130
	v_cvt_pk_bf16_f32 v42, v88, v89
	v_exp_f32_e32 v88, v16
	v_sub_f32_e32 v16, v20, v130
	s_waitcnt lgkmcnt(1)
	v_mfma_f32_32x32x16_bf16 v[64:79], v[80:83], v[38:41], v[64:79]
	v_cvt_pk_bf16_f32 v43, v90, v91
	v_cvt_pk_bf16_f32 v44, v92, v93
	v_cvt_pk_bf16_f32 v45, v94, v95
	ds_read2_b64 v[80:83], v33 offset0:20 offset1:22
	v_exp_f32_e32 v89, v16
	v_sub_f32_e32 v16, v21, v130
	v_exp_f32_e32 v90, v16
	ds_read2_b64 v[16:19], v32 offset0:20 offset1:22
	s_waitcnt lgkmcnt(2)
	v_mfma_f32_32x32x16_bf16 v[48:63], v[34:37], v[38:41], v[48:63]
	v_sub_f32_e32 v20, v22, v130
	v_cvt_pk_bf16_f32 v34, v139, v147
	v_cvt_pk_bf16_f32 v35, v149, v151
	v_cvt_pk_bf16_f32 v36, v153, v166
	v_cvt_pk_bf16_f32 v37, v167, v168
	ds_read2_b64 v[38:41], v33 offset0:24 offset1:26
	v_mov_b32_e32 v147, v141
	s_waitcnt lgkmcnt(2)
	v_mfma_f32_32x32x16_bf16 v[64:79], v[80:83], v[42:45], v[64:79]
	v_exp_f32_e32 v80, v20
	v_sub_f32_e32 v20, v24, v130
	v_mov_b32_e32 v149, v141
	v_mov_b32_e32 v151, v141
	v_mov_b32_e32 v153, v141
	s_waitcnt lgkmcnt(1)
	v_mfma_f32_32x32x16_bf16 v[48:63], v[16:19], v[42:45], v[48:63]
	v_add_f32_e32 v16, v88, v87
	v_add_f32_e32 v16, v89, v16
	v_add_f32_e32 v16, v90, v16
	v_add_f32_e32 v42, v80, v16
	v_sub_f32_e32 v16, v23, v130
	v_exp_f32_e32 v43, v16
	ds_read2_b64 v[16:19], v32 offset0:24 offset1:26
	v_exp_f32_e32 v44, v20
	s_waitcnt lgkmcnt(0)
	v_mfma_f32_32x32x16_bf16 v[48:63], v[16:19], v[34:37], v[48:63]
	v_add_f32_e32 v16, v43, v42
	v_add_f32_e32 v24, v44, v16
	v_sub_f32_e32 v16, v25, v130
	v_exp_f32_e32 v42, v16
	v_sub_f32_e32 v16, v26, v130
	v_cvt_pk_bf16_f32 v20, v169, v170
	v_cvt_pk_bf16_f32 v21, v171, v172
	v_cvt_pk_bf16_f32 v22, v173, v174
	v_cvt_pk_bf16_f32 v23, v175, v176
	v_exp_f32_e32 v45, v16
	ds_read2_b64 v[16:19], v32 offset0:28 offset1:30
	v_mfma_f32_32x32x16_bf16 v[64:79], v[38:41], v[34:37], v[64:79]
	ds_read2_b64 v[38:41], v33 offset0:28 offset1:30
	v_cvt_pk_bf16_f32 v34, v177, v178
	v_cvt_pk_bf16_f32 v35, v179, v180
	v_cvt_pk_bf16_f32 v36, v181, v182
	v_cvt_pk_bf16_f32 v37, v183, v184
	v_add_f32_e32 v24, v42, v24
	v_add_f32_e32 v81, v45, v24
	s_waitcnt lgkmcnt(1)
	v_mfma_f32_32x32x16_bf16 v[48:63], v[16:19], v[20:23], v[48:63]
	v_sub_f32_e32 v16, v27, v130
	v_exp_f32_e32 v82, v16
	v_sub_f32_e32 v16, v28, v130
	v_exp_f32_e32 v83, v16
	v_sub_f32_e32 v16, v29, v130
	v_exp_f32_e32 v87, v16
	ds_read2_b64 v[16:19], v32 offset0:32 offset1:34
	s_waitcnt lgkmcnt(1)
	v_mfma_f32_32x32x16_bf16 v[64:79], v[38:41], v[20:23], v[64:79]
	ds_read2_b64 v[38:41], v33 offset0:32 offset1:34
	v_sub_f32_e32 v20, v30, v130
	s_waitcnt lgkmcnt(0)
	v_mfma_f32_32x32x16_bf16 v[64:79], v[38:41], v[34:37], v[64:79]
	v_exp_f32_e32 v38, v20
	v_cvt_pk_bf16_f32 v20, v185, v186
	v_cvt_pk_bf16_f32 v21, v187, v188
	v_cvt_pk_bf16_f32 v22, v189, v190
	v_cvt_pk_bf16_f32 v23, v191, v192
	ds_read2_b64 v[24:27], v33 offset0:36 offset1:38
	v_mfma_f32_32x32x16_bf16 v[48:63], v[16:19], v[34:37], v[48:63]
	v_add_f32_e32 v16, v82, v81
	v_add_f32_e32 v16, v83, v16
	v_add_f32_e32 v16, v87, v16
	v_add_f32_e32 v34, v38, v16
	v_sub_f32_e32 v16, v31, v130
	v_exp_f32_e32 v35, v16
	ds_read2_b64 v[16:19], v32 offset0:36 offset1:38
	s_waitcnt lgkmcnt(1)
	v_mfma_f32_32x32x16_bf16 v[64:79], v[24:27], v[20:23], v[64:79]
	v_cvt_pk_bf16_f32 v24, v193, v194
	v_cvt_pk_bf16_f32 v25, v195, v196
	v_cvt_pk_bf16_f32 v26, v197, v198
	v_cvt_pk_bf16_f32 v27, v199, v112
	ds_read2_b64 v[28:31], v33 offset0:40 offset1:42
	v_exp_f32_e32 v36, v0
	v_add_f32_e32 v0, v35, v34
	s_waitcnt lgkmcnt(1)
	v_mfma_f32_32x32x16_bf16 v[48:63], v[16:19], v[20:23], v[48:63]
	v_exp_f32_e32 v34, v1
	v_sub_f32_e32 v1, v2, v130
	ds_read2_b64 v[16:19], v32 offset0:40 offset1:42
	v_exp_f32_e32 v37, v1
	v_add_f32_e32 v0, v36, v0
	v_add_f32_e32 v0, v34, v0
	v_cvt_pk_bf16_f32 v20, v113, v114
	v_add_f32_e32 v39, v37, v0
	v_sub_f32_e32 v0, v3, v130
	v_exp_f32_e32 v40, v0
	v_sub_f32_e32 v0, v4, v130
	s_waitcnt lgkmcnt(1)
	v_mfma_f32_32x32x16_bf16 v[64:79], v[28:31], v[24:27], v[64:79]
	v_cvt_pk_bf16_f32 v21, v115, v96
	v_cvt_pk_bf16_f32 v22, v97, v98
	v_cvt_pk_bf16_f32 v23, v46, v47
	ds_read2_b64 v[28:31], v33 offset0:44 offset1:46
	v_exp_f32_e32 v41, v0
	v_sub_f32_e32 v0, v5, v130
	v_exp_f32_e32 v46, v0
	ds_read2_b64 v[0:3], v32 offset0:44 offset1:46
	s_waitcnt lgkmcnt(2)
	v_mfma_f32_32x32x16_bf16 v[48:63], v[16:19], v[24:27], v[48:63]
	v_sub_f32_e32 v4, v6, v130
	v_cvt_pk_bf16_f32 v16, v85, v84
	v_cvt_pk_bf16_f32 v17, v86, v88
	v_cvt_pk_bf16_f32 v18, v89, v90
	v_cvt_pk_bf16_f32 v19, v80, v43
	ds_read2_b64 v[24:27], v33 offset0:48 offset1:50
	s_waitcnt lgkmcnt(2)
	v_mfma_f32_32x32x16_bf16 v[64:79], v[28:31], v[20:23], v[64:79]
	v_exp_f32_e32 v28, v4
	v_sub_f32_e32 v4, v8, v130
	v_sub_f32_e32 v8, v11, v130
	s_waitcnt lgkmcnt(1)
	v_mfma_f32_32x32x16_bf16 v[48:63], v[0:3], v[20:23], v[48:63]
	v_add_f32_e32 v0, v40, v39
	v_add_f32_e32 v0, v41, v0
	v_add_f32_e32 v0, v46, v0
	v_add_f32_e32 v29, v28, v0
	v_sub_f32_e32 v0, v7, v130
	v_exp_f32_e32 v30, v0
	ds_read2_b64 v[0:3], v32 offset0:48 offset1:50
	s_waitcnt lgkmcnt(1)
	v_mfma_f32_32x32x16_bf16 v[64:79], v[24:27], v[16:19], v[64:79]
	v_exp_f32_e32 v24, v4
	v_cvt_pk_bf16_f32 v4, v44, v42
	v_cvt_pk_bf16_f32 v5, v45, v82
	v_cvt_pk_bf16_f32 v6, v83, v87
	v_cvt_pk_bf16_f32 v7, v38, v35
	ds_read2_b64 v[20:23], v33 offset0:52 offset1:54
	s_waitcnt lgkmcnt(1)
	v_mfma_f32_32x32x16_bf16 v[48:63], v[0:3], v[16:19], v[48:63]
	v_add_f32_e32 v0, v30, v29
	v_add_f32_e32 v25, v24, v0
	v_sub_f32_e32 v0, v9, v130
	v_exp_f32_e32 v26, v0
	v_sub_f32_e32 v0, v10, v130
	v_exp_f32_e32 v27, v0
	ds_read2_b64 v[0:3], v32 offset0:52 offset1:54
	s_waitcnt lgkmcnt(0)
	v_mfma_f32_32x32x16_bf16 v[48:63], v[0:3], v[4:7], v[48:63]
	v_sub_f32_e32 v0, v12, v130
	v_mfma_f32_32x32x16_bf16 v[64:79], v[20:23], v[4:7], v[64:79]
	v_exp_f32_e32 v21, v0
	v_sub_f32_e32 v0, v13, v130
	v_exp_f32_e32 v22, v0
	v_sub_f32_e32 v0, v14, v130
	v_exp_f32_e32 v20, v8
	v_cvt_pk_bf16_f32 v8, v36, v34
	v_cvt_pk_bf16_f32 v9, v37, v40
	v_cvt_pk_bf16_f32 v10, v41, v46
	v_cvt_pk_bf16_f32 v11, v28, v30
	v_exp_f32_e32 v23, v0
	ds_read2_b64 v[0:3], v32 offset0:56 offset1:58
	ds_read2_b64 v[16:19], v33 offset0:56 offset1:58
	s_waitcnt lgkmcnt(1)
	v_mfma_f32_32x32x16_bf16 v[48:63], v[0:3], v[8:11], v[48:63]
	v_add_f32_e32 v0, v26, v25
	v_add_f32_e32 v0, v27, v0
	v_add_f32_e32 v0, v20, v0
	v_add_f32_e32 v0, v21, v0
	v_sub_f32_e32 v4, v15, v130
	v_add_f32_e32 v0, v22, v0
	s_waitcnt lgkmcnt(0)
	v_mfma_f32_32x32x16_bf16 v[64:79], v[16:19], v[8:11], v[64:79]
	v_exp_f32_e32 v16, v4
	v_cvt_pk_bf16_f32 v4, v24, v26
	v_cvt_pk_bf16_f32 v5, v27, v20
	v_cvt_pk_bf16_f32 v6, v21, v22
	v_cvt_pk_bf16_f32 v7, v23, v16
	v_add_f32_e32 v8, v23, v0
	ds_read2_b64 v[0:3], v32 offset0:60 offset1:62
	ds_read2_b64 v[12:15], v33 offset0:60 offset1:62
	s_waitcnt lgkmcnt(1)
	v_mfma_f32_32x32x16_bf16 v[48:63], v[0:3], v[4:7], v[48:63]
	v_lshl_add_u64 v[0:1], v[128:129], 0, v[146:147]
	v_add_f32_e32 v10, v16, v8
	ds_bpermute_b32 v11, v155, v10
	v_lshl_add_u64 v[8:9], s[18:19], 0, v[140:141]
	v_lshl_add_u64 v[8:9], v[8:9], 0, s[6:7]
	s_waitcnt lgkmcnt(0)
	v_add_f32_e32 v10, v10, v11
	v_mfma_f32_32x32x16_bf16 v[64:79], v[12:15], v[4:7], v[64:79]
	v_lshl_add_u64 v[4:5], v[0:1], 0, v[148:149]
	global_load_dwordx4 v[0:3], v[4:5], off
	global_load_dwordx4 v[136:139], v[4:5], off offset:32
	global_load_dwordx4 v[132:135], v[4:5], off offset:64
	global_load_dwordx4 v[128:131], v[4:5], off offset:96
	v_div_scale_f32 v6, s[18:19], v10, v10, 1.0
	v_rcp_f32_e32 v7, v6
	s_nop 0
	v_fma_f32 v4, -v6, v7, 1.0
	v_fmac_f32_e32 v7, v4, v7
	v_div_scale_f32 v4, vcc, 1.0, v10, 1.0
	v_mul_f32_e32 v5, v4, v7
	v_fma_f32 v11, -v6, v5, v4
	v_fmac_f32_e32 v5, v11, v7
	v_fma_f32 v4, -v6, v5, v4
	v_div_fmas_f32 v4, v4, v7, v5
	v_div_fixup_f32 v10, v4, v10, 1.0
	v_lshl_add_u64 v[4:5], v[8:9], 0, v[150:151]
	v_lshl_add_u64 v[4:5], v[4:5], 0, v[152:153]
	v_lshl_add_u64 v[6:7], v[4:5], 0, s[14:15]
	v_mul_f32_e32 v8, v64, v10
	v_mul_f32_e32 v9, v65, v10
	v_add_co_u32_e32 v4, vcc, s28, v4
	v_cvt_pk_bf16_f32 v8, v8, v9
	v_mul_f32_e32 v9, v66, v10
	s_nop 0
	v_addc_co_u32_e32 v5, vcc, 0, v5, vcc
	v_mul_f32_e32 v11, v67, v10
	v_cvt_pk_bf16_f32 v9, v9, v11
	global_store_dwordx2 v[4:5], v[8:9], off offset:1536
	v_mul_f32_e32 v4, v68, v10
	v_mul_f32_e32 v5, v69, v10
	v_cvt_pk_bf16_f32 v4, v4, v5
	v_mul_f32_e32 v5, v70, v10
	v_mul_f32_e32 v8, v71, v10
	v_cvt_pk_bf16_f32 v5, v5, v8
	global_store_dwordx2 v[6:7], v[4:5], off offset:16
	v_mul_f32_e32 v4, v72, v10
	v_mul_f32_e32 v5, v73, v10
	v_cvt_pk_bf16_f32 v4, v4, v5
	v_mul_f32_e32 v5, v74, v10
	v_mul_f32_e32 v8, v75, v10
	v_cvt_pk_bf16_f32 v5, v5, v8
	global_store_dwordx2 v[6:7], v[4:5], off offset:32
	v_mul_f32_e32 v4, v76, v10
	v_mul_f32_e32 v5, v77, v10
	v_cvt_pk_bf16_f32 v4, v4, v5
	v_mul_f32_e32 v5, v78, v10
	v_mul_f32_e32 v8, v79, v10
	v_cvt_pk_bf16_f32 v5, v5, v8
	global_store_dwordx2 v[6:7], v[4:5], off offset:48
	v_mul_f32_e32 v4, v48, v10
	v_mul_f32_e32 v5, v49, v10
	v_cvt_pk_bf16_f32 v4, v4, v5
	v_mul_f32_e32 v5, v50, v10
	v_mul_f32_e32 v8, v51, v10
	v_cvt_pk_bf16_f32 v5, v5, v8
	global_store_dwordx2 v[6:7], v[4:5], off offset:64
	v_mul_f32_e32 v4, v52, v10
	v_mul_f32_e32 v5, v53, v10
	v_cvt_pk_bf16_f32 v4, v4, v5
	v_mul_f32_e32 v5, v54, v10
	v_mul_f32_e32 v8, v55, v10
	v_cvt_pk_bf16_f32 v5, v5, v8
	global_store_dwordx2 v[6:7], v[4:5], off offset:80
	v_mul_f32_e32 v4, v56, v10
	v_mul_f32_e32 v5, v57, v10
	v_cvt_pk_bf16_f32 v4, v4, v5
	v_mul_f32_e32 v5, v58, v10
	v_mul_f32_e32 v8, v59, v10
	v_cvt_pk_bf16_f32 v5, v5, v8
	global_store_dwordx2 v[6:7], v[4:5], off offset:96
	v_mul_f32_e32 v4, v60, v10
	v_mul_f32_e32 v5, v61, v10
	v_cvt_pk_bf16_f32 v4, v4, v5
	v_mul_f32_e32 v5, v62, v10
	s_and_b64 vcc, s[16:17], exec
	v_mul_f32_e32 v8, v63, v10
	v_cvt_pk_bf16_f32 v5, v5, v8
	global_store_dwordx2 v[6:7], v[4:5], off offset:112
	s_barrier
	s_cbranch_vccnz .LBB0_553

.LBB0_564:
	s_add_i32 s22, s23, 1
	s_lshl_b32 s8, s22, 9
	s_cmp_lg_u32 s23, 7
	s_cselect_b32 s8, s8, 0xe00
	s_mul_i32 s10, s8, 0x300
	s_ashr_i32 s9, s10, 31
	s_mov_b32 s8, s10
	v_lshl_add_u64 v[84:85], s[8:9], 1, v[110:111]
	v_add_co_u32_e32 v2, vcc, s52, v84
	s_waitcnt vmcnt(15)
	ds_write_b128 v222, v[32:35] offset:33792
	s_waitcnt vmcnt(14)
	ds_write_b128 v222, v[36:39] offset:34880
	s_waitcnt vmcnt(13)
	ds_write_b128 v222, v[40:43] offset:35968
	s_waitcnt vmcnt(12)
	ds_write_b128 v222, v[44:47] offset:37056
	s_waitcnt vmcnt(11)
	ds_write_b128 v222, v[48:51] offset:38144
	s_waitcnt vmcnt(10)
	ds_write_b128 v222, v[56:59] offset:39232
	s_waitcnt vmcnt(9)
	ds_write_b128 v222, v[64:67] offset:40320
	s_waitcnt vmcnt(8)
	ds_write_b128 v222, v[72:75] offset:41408
	v_lshl_add_u64 v[0:1], s[10:11], 1, v[110:111]
	v_addc_co_u32_e32 v3, vcc, 0, v85, vcc
	global_load_dwordx4 v[32:35], v[0:1], off
	global_load_dwordx4 v[36:39], v[2:3], off offset:2048
	v_add_co_u32_e32 v0, vcc, s53, v84
	v_add_u32_e32 v86, v105, v104
	s_nop 0
	v_addc_co_u32_e32 v1, vcc, 0, v85, vcc
	v_add_co_u32_e32 v2, vcc, s54, v84
	s_lshl_b32 s8, s23, 13
	s_nop 0
	v_addc_co_u32_e32 v3, vcc, 0, v85, vcc
	global_load_dwordx4 v[40:43], v[0:1], off
	global_load_dwordx4 v[44:47], v[2:3], off offset:2048
	v_add_co_u32_e32 v0, vcc, s55, v84
	s_and_b32 s10, s8, 0x2000
	s_nop 0
	v_addc_co_u32_e32 v1, vcc, 0, v85, vcc
	v_add_co_u32_e32 v2, vcc, s56, v84
	s_cmp_eq_u32 s23, 0
	s_nop 0
	v_addc_co_u32_e32 v3, vcc, 0, v85, vcc
	global_load_dwordx4 v[48:51], v[0:1], off
	global_load_dwordx4 v[56:59], v[2:3], off offset:2048
	v_add_co_u32_e32 v0, vcc, s57, v84
	s_nop 1
	v_addc_co_u32_e32 v1, vcc, 0, v85, vcc
	v_add_co_u32_e32 v2, vcc, s58, v84
	s_nop 1
	v_addc_co_u32_e32 v3, vcc, 0, v85, vcc
	global_load_dwordx4 v[64:67], v[0:1], off
	global_load_dwordx4 v[72:75], v[2:3], off offset:2048
	s_waitcnt lgkmcnt(0)
	ds_read_b128 v[0:3], v223 offset:33792
	ds_read_b128 v[4:7], v86
	ds_read_b128 v[116:119], v223 offset:33824
	ds_read_b128 v[120:123], v86 offset:32
	s_waitcnt lgkmcnt(2)
	v_mfma_f32_32x32x16_bf16 v[16:31], v[0:3], v[4:7], 0
	ds_read_b128 v[4:7], v86 offset:8704
	ds_read_b128 v[124:127], v86 offset:8736
	s_waitcnt lgkmcnt(1)
	v_mfma_f32_32x32x16_bf16 v[0:15], v[0:3], v[4:7], 0
	v_mfma_f32_32x32x16_bf16 v[16:31], v[116:119], v[120:123], v[16:31]
	s_waitcnt lgkmcnt(0)
	v_mfma_f32_32x32x16_bf16 v[0:15], v[116:119], v[124:127], v[0:15]
	ds_read_b128 v[116:119], v223 offset:33856
	ds_read_b128 v[120:123], v86 offset:64
	ds_read_b128 v[124:127], v223 offset:33888
	ds_read_b128 v[128:131], v86 offset:96
	s_waitcnt lgkmcnt(2)
	v_mfma_f32_32x32x16_bf16 v[16:31], v[116:119], v[120:123], v[16:31]
	ds_read_b128 v[120:123], v86 offset:8768
	ds_read_b128 v[132:135], v86 offset:8800
	s_waitcnt lgkmcnt(1)
	v_mfma_f32_32x32x16_bf16 v[0:15], v[116:119], v[120:123], v[0:15]
	v_mfma_f32_32x32x16_bf16 v[16:31], v[124:127], v[128:131], v[16:31]
	s_waitcnt lgkmcnt(0)
	v_mfma_f32_32x32x16_bf16 v[0:15], v[124:127], v[132:135], v[0:15]
	ds_read_b128 v[116:119], v223 offset:33920
	ds_read_b128 v[120:123], v86 offset:128
	ds_read_b128 v[124:127], v223 offset:33952
	ds_read_b128 v[128:131], v86 offset:160
	s_waitcnt lgkmcnt(2)
	v_mfma_f32_32x32x16_bf16 v[16:31], v[116:119], v[120:123], v[16:31]
	ds_read_b128 v[120:123], v86 offset:8832
	ds_read_b128 v[132:135], v86 offset:8864
	s_waitcnt lgkmcnt(1)
	v_mfma_f32_32x32x16_bf16 v[0:15], v[116:119], v[120:123], v[0:15]
	v_mfma_f32_32x32x16_bf16 v[16:31], v[124:127], v[128:131], v[16:31]
	s_waitcnt lgkmcnt(0)
	v_mfma_f32_32x32x16_bf16 v[0:15], v[124:127], v[132:135], v[0:15]
	ds_read_b128 v[116:119], v223 offset:33984
	ds_read_b128 v[120:123], v86 offset:192
	ds_read_b128 v[124:127], v223 offset:34016
	ds_read_b128 v[128:131], v86 offset:224
	s_waitcnt lgkmcnt(2)
	v_mfma_f32_32x32x16_bf16 v[16:31], v[116:119], v[120:123], v[16:31]
	ds_read_b128 v[120:123], v86 offset:8896
	s_waitcnt lgkmcnt(1)
	v_mfma_f32_32x32x16_bf16 v[16:31], v[124:127], v[128:131], v[16:31]
	ds_read_b128 v[128:131], v86 offset:8928
	s_waitcnt lgkmcnt(1)
	v_mfma_f32_32x32x16_bf16 v[0:15], v[116:119], v[120:123], v[0:15]
	s_nop 8
	v_add_f32_e32 v16, v225, v16
	v_mul_f32_e32 v16, 0xbfb8aa3b, v16
	v_exp_f32_e32 v16, v16
	v_add_f32_e32 v17, v225, v17
	v_mul_f32_e32 v17, 0xbfb8aa3b, v17
	v_exp_f32_e32 v17, v17
	v_add_f32_e32 v16, 1.0, v16
	v_rcp_f32_e32 v16, v16
	s_waitcnt lgkmcnt(0)
	v_mfma_f32_32x32x16_bf16 v[0:15], v[124:127], v[128:131], v[0:15]
	v_add_f32_e32 v18, v225, v18
	v_mul_f32_e32 v18, 0xbfb8aa3b, v18
	v_mul_f32_e32 v16, v227, v16
	v_exp_f32_e32 v116, v16
	v_exp_f32_e32 v18, v18
	v_add_f32_e32 v19, v225, v19
	v_mul_f32_e32 v19, 0xbfb8aa3b, v19
	v_fma_f32 v16, -v116, v116, 1.0
	s_nop 1
	s_nop 1
	v_add_f32_e32 v0, v226, v0
	v_mul_f32_e32 v0, 0xbfb8aa3b, v0
	v_exp_f32_e32 v0, v0
	v_add_f32_e32 v2, v226, v2
	v_mul_f32_e32 v2, 0xbfb8aa3b, v2
	v_add_f32_e32 v0, 1.0, v0
	v_rcp_f32_e32 v0, v0
	v_exp_f32_e32 v2, v2
	s_cselect_b64 s[8:9], -1, 0
	s_and_b64 s[8:9], s[8:9], s[6:7]
	s_and_b64 s[8:9], s[8:9], s[12:13]
	v_sqrt_f32_e32 v16, v16
	s_nop 0
	v_cndmask_b32_e64 v16, v16, 1.0, s[8:9]
	v_mul_f32_e32 v117, v0, v16
	v_add_f32_e32 v0, 1.0, v17
	v_rcp_f32_e32 v0, v0
	ds_read_u16 v16, v228 offset:33792
	ds_read_u16 v17, v228 offset:34064
	ds_read_u16 v125, v228 offset:34336
	ds_read_u16 v129, v228 offset:34608
	ds_read_u16 v133, v228 offset:34880
	ds_read_u16 v137, v228 offset:35152
	ds_read_u16 v141, v228 offset:35424
	ds_read_u16 v145, v228 offset:35696
	s_waitcnt lgkmcnt(7)
	v_lshlrev_b32_e32 v103, 16, v16
	v_pk_mul_f32 v[120:121], v[116:117], v[102:103]
	v_mul_f32_e32 v0, v227, v0
	v_exp_f32_e32 v118, v0
	v_add_f32_e32 v0, v226, v1
	v_mul_f32_e32 v0, 0xbfb8aa3b, v0
	v_exp_f32_e32 v0, v0
	v_fma_f32 v1, -v118, v118, 1.0
	v_add_f32_e32 v0, 1.0, v0
	v_rcp_f32_e32 v0, v0
	v_add_f32_e32 v2, 1.0, v2
	v_rcp_f32_e32 v2, v2
	v_exp_f32_e32 v19, v19
	s_waitcnt lgkmcnt(5)
	v_lshlrev_b32_e32 v125, 16, v125
	s_waitcnt lgkmcnt(4)
	v_lshlrev_b32_e32 v129, 16, v129
	s_waitcnt lgkmcnt(3)
	v_lshlrev_b32_e32 v133, 16, v133
	v_lshlrev_b32_e32 v119, 16, v17
	s_waitcnt lgkmcnt(2)
	v_lshlrev_b32_e32 v137, 16, v137
	v_sqrt_f32_e32 v1, v1
	s_nop 0
	v_mul_f32_e32 v16, v0, v1
	v_add_f32_e32 v0, 1.0, v18
	v_rcp_f32_e32 v17, v0
	v_pk_fma_f32 v[0:1], v[116:117], v[102:103], v[120:121] op_sel:[0,0,1] op_sel_hi:[1,1,0]
	v_mul_f32_e32 v18, v116, v118
	v_mov_b32_e32 v1, v16
	v_mul_f32_e32 v16, v227, v17
	v_exp_f32_e32 v124, v16
	v_pk_mul_f32 v[122:123], v[0:1], v[118:119]
	s_waitcnt lgkmcnt(1)
	v_lshlrev_b32_e32 v141, 16, v141
	v_pk_fma_f32 v[0:1], v[0:1], v[118:119], v[122:123] op_sel:[0,0,1] op_sel_hi:[1,1,0]
	v_fma_f32 v16, -v124, v124, 1.0
	s_waitcnt lgkmcnt(0)
	v_lshlrev_b32_e32 v145, 16, v145
	s_nop 0
	s_nop 0
	s_nop 1
	s_nop 1
	v_sqrt_f32_e32 v16, v16
	s_nop 0
	v_mul_f32_e32 v2, v2, v16
	v_add_f32_e32 v16, 1.0, v19
	v_rcp_f32_e32 v16, v16
	v_mov_b32_e32 v1, v2
	v_mul_f32_e32 v17, v18, v124
	v_pk_mul_f32 v[126:127], v[0:1], v[124:125]
	v_mul_f32_e32 v2, v227, v16
	v_exp_f32_e32 v128, v2
	v_add_f32_e32 v2, v226, v3
	v_mul_f32_e32 v2, 0xbfb8aa3b, v2
	v_exp_f32_e32 v2, v2
	v_fma_f32 v3, -v128, v128, 1.0
	v_add_f32_e32 v2, 1.0, v2
	v_rcp_f32_e32 v2, v2
	v_pk_fma_f32 v[0:1], v[0:1], v[124:125], v[126:127] op_sel:[0,0,1] op_sel_hi:[1,1,0]
	s_nop 0
	s_nop 1
	v_add_f32_e32 v18, v225, v20
	v_mul_f32_e32 v18, 0xbfb8aa3b, v18
	v_exp_f32_e32 v18, v18
	s_nop 1
	v_sqrt_f32_e32 v3, v3
	s_nop 0
	v_mul_f32_e32 v2, v2, v3
	v_add_f32_e32 v3, 1.0, v18
	v_rcp_f32_e32 v3, v3
	v_mov_b32_e32 v1, v2
	v_mul_f32_e32 v16, v17, v128
	v_pk_mul_f32 v[130:131], v[0:1], v[128:129]
	v_mul_f32_e32 v2, v227, v3
	v_exp_f32_e32 v132, v2
	v_add_f32_e32 v2, v226, v4
	v_mul_f32_e32 v2, 0xbfb8aa3b, v2
	v_exp_f32_e32 v2, v2
	v_fma_f32 v3, -v132, v132, 1.0
	v_add_f32_e32 v2, 1.0, v2
	v_rcp_f32_e32 v2, v2
	v_pk_fma_f32 v[0:1], v[0:1], v[128:129], v[130:131] op_sel:[0,0,1] op_sel_hi:[1,1,0]
	s_nop 0
	s_nop 1
	v_add_f32_e32 v17, v225, v21
	v_mul_f32_e32 v17, 0xbfb8aa3b, v17
	v_exp_f32_e32 v17, v17
	s_nop 1
	v_sqrt_f32_e32 v3, v3
	s_nop 0
	v_mul_f32_e32 v2, v2, v3
	v_add_f32_e32 v3, 1.0, v17
	v_rcp_f32_e32 v3, v3
	v_mov_b32_e32 v1, v2
	v_pk_mul_f32 v[134:135], v[0:1], v[132:133]
	v_mul_f32_e32 v2, v227, v3
	v_exp_f32_e32 v136, v2
	v_add_f32_e32 v2, v226, v5
	v_mul_f32_e32 v5, v16, v132
	v_mul_f32_e32 v2, 0xbfb8aa3b, v2
	v_fma_f32 v3, -v136, v136, 1.0
	v_exp_f32_e32 v2, v2
	v_pk_fma_f32 v[0:1], v[0:1], v[132:133], v[134:135] op_sel:[0,0,1] op_sel_hi:[1,1,0]
	v_add_f32_e32 v2, 1.0, v2
	v_rcp_f32_e32 v2, v2
	v_mul_f32_e32 v5, v5, v136
	s_nop 0
	s_nop 1
	v_add_f32_e32 v16, v225, v22
	v_mul_f32_e32 v16, 0xbfb8aa3b, v16
	v_exp_f32_e32 v16, v16
	s_nop 1
	v_sqrt_f32_e32 v3, v3
	s_nop 0
	v_mul_f32_e32 v2, v2, v3
	v_add_f32_e32 v3, 1.0, v16
	v_rcp_f32_e32 v3, v3
	v_mov_b32_e32 v1, v2
	v_pk_mul_f32 v[138:139], v[0:1], v[136:137]
	v_mul_f32_e32 v2, v227, v3
	v_exp_f32_e32 v140, v2
	v_add_f32_e32 v2, v226, v6
	v_mul_f32_e32 v2, 0xbfb8aa3b, v2
	v_exp_f32_e32 v2, v2
	v_fma_f32 v3, -v140, v140, 1.0
	v_add_f32_e32 v2, 1.0, v2
	v_rcp_f32_e32 v2, v2
	v_pk_fma_f32 v[0:1], v[0:1], v[136:137], v[138:139] op_sel:[0,0,1] op_sel_hi:[1,1,0]
	v_mul_f32_e32 v5, v5, v140
	s_nop 0
	s_nop 1
	v_add_f32_e32 v6, v225, v23
	v_mul_f32_e32 v6, 0xbfb8aa3b, v6
	v_exp_f32_e32 v6, v6
	s_nop 1
	v_sqrt_f32_e32 v3, v3
	s_nop 0
	v_mul_f32_e32 v2, v2, v3
	v_add_f32_e32 v3, 1.0, v6
	v_rcp_f32_e32 v3, v3
	v_mov_b32_e32 v1, v2
	v_pk_mul_f32 v[142:143], v[0:1], v[140:141]
	v_mul_f32_e32 v2, v227, v3
	v_exp_f32_e32 v144, v2
	v_add_f32_e32 v2, v226, v7
	v_mul_f32_e32 v2, 0xbfb8aa3b, v2
	v_exp_f32_e32 v2, v2
	v_fma_f32 v3, -v144, v144, 1.0
	v_add_f32_e32 v2, 1.0, v2
	v_rcp_f32_e32 v2, v2
	v_pk_fma_f32 v[0:1], v[0:1], v[140:141], v[142:143] op_sel:[0,0,1] op_sel_hi:[1,1,0]
	v_mul_f32_e32 v5, v5, v144
	v_mov_b32_e32 v142, 0
	s_nop 0
	s_nop 1
	v_add_f32_e32 v6, v225, v24
	v_mul_f32_e32 v6, 0xbfb8aa3b, v6
	v_exp_f32_e32 v6, v6
	s_nop 1
	v_sqrt_f32_e32 v3, v3
	s_nop 0
	v_mul_f32_e32 v2, v2, v3
	v_add_f32_e32 v3, 1.0, v6
	v_rcp_f32_e32 v3, v3
	v_mov_b32_e32 v1, v2
	v_pk_mul_f32 v[146:147], v[0:1], v[144:145]
	v_mul_f32_e32 v2, v227, v3
	v_exp_f32_e32 v148, v2
	v_add_f32_e32 v2, v226, v8
	v_mul_f32_e32 v2, 0xbfb8aa3b, v2
	v_exp_f32_e32 v2, v2
	v_fma_f32 v3, -v148, v148, 1.0
	v_add_f32_e32 v2, 1.0, v2
	v_rcp_f32_e32 v2, v2
	v_pk_fma_f32 v[0:1], v[0:1], v[144:145], v[146:147] op_sel:[0,0,1] op_sel_hi:[1,1,0]
	v_mul_f32_e32 v5, v5, v148
	s_nop 0
	s_nop 1
	s_nop 1
	v_sqrt_f32_e32 v3, v3
	s_nop 0
	v_mul_f32_e32 v2, v2, v3
	v_add_f32_e32 v3, v225, v25
	v_mul_f32_e32 v3, 0xbfb8aa3b, v3
	v_exp_f32_e32 v3, v3
	v_mov_b32_e32 v1, v2
	ds_read_u16 v4, v228 offset:35968
	ds_read_u16 v6, v228 offset:36240
	ds_read_u16 v7, v228 offset:36512
	ds_read_u16 v8, v228 offset:36784
	ds_read_u16 v16, v228 offset:37056
	ds_read_u16 v17, v228 offset:37328
	ds_read_u16 v18, v228 offset:37600
	ds_read_u16 v19, v228 offset:37872
	s_waitcnt lgkmcnt(7)
	v_lshlrev_b32_e32 v149, 16, v4
	v_add_f32_e32 v3, 1.0, v3
	v_rcp_f32_e32 v3, v3
	v_pk_mul_f32 v[150:151], v[0:1], v[148:149]
	s_waitcnt lgkmcnt(6)
	v_lshlrev_b32_e32 v153, 16, v6
	v_pk_fma_f32 v[0:1], v[0:1], v[148:149], v[150:151] op_sel:[0,0,1] op_sel_hi:[1,1,0]
	v_mul_f32_e32 v2, v227, v3
	v_exp_f32_e32 v152, v2
	v_add_f32_e32 v2, v226, v9
	v_mul_f32_e32 v2, 0xbfb8aa3b, v2
	v_exp_f32_e32 v2, v2
	v_fma_f32 v3, -v152, v152, 1.0
	v_add_f32_e32 v2, 1.0, v2
	v_rcp_f32_e32 v2, v2
	s_waitcnt lgkmcnt(5)
	v_lshlrev_b32_e32 v157, 16, v7
	s_waitcnt lgkmcnt(4)
	v_lshlrev_b32_e32 v161, 16, v8
	s_waitcnt lgkmcnt(3)
	v_lshlrev_b32_e32 v165, 16, v16
	s_waitcnt lgkmcnt(2)
	v_lshlrev_b32_e32 v169, 16, v17
	v_mul_f32_e32 v5, v5, v152
	s_waitcnt lgkmcnt(1)
	v_lshlrev_b32_e32 v173, 16, v18
	v_add_f32_e32 v9, v225, v26
	v_mul_f32_e32 v9, 0xbfb8aa3b, v9
	v_exp_f32_e32 v9, v9
	s_waitcnt lgkmcnt(0)
	v_lshlrev_b32_e32 v177, 16, v19
	v_mov_b32_e32 v150, v107
	v_sqrt_f32_e32 v3, v3
	s_nop 0
	v_mul_f32_e32 v2, v2, v3
	v_add_f32_e32 v3, 1.0, v9
	v_rcp_f32_e32 v3, v3
	v_mov_b32_e32 v1, v2
	v_pk_mul_f32 v[154:155], v[0:1], v[152:153]
	v_mul_f32_e32 v2, v227, v3
	v_exp_f32_e32 v156, v2
	v_add_f32_e32 v2, v226, v10
	v_mul_f32_e32 v2, 0xbfb8aa3b, v2
	v_exp_f32_e32 v2, v2
	v_fma_f32 v3, -v156, v156, 1.0
	v_add_f32_e32 v2, 1.0, v2
	v_rcp_f32_e32 v2, v2
	v_pk_fma_f32 v[0:1], v[0:1], v[152:153], v[154:155] op_sel:[0,0,1] op_sel_hi:[1,1,0]
	v_mul_f32_e32 v5, v5, v156
	v_mov_b32_e32 v153, 0
	s_nop 0
	s_nop 1
	v_add_f32_e32 v6, v225, v27
	v_mul_f32_e32 v6, 0xbfb8aa3b, v6
	v_exp_f32_e32 v6, v6
	s_nop 1
	v_sqrt_f32_e32 v3, v3
	s_nop 0
	v_mul_f32_e32 v2, v2, v3
	v_add_f32_e32 v3, 1.0, v6
	v_rcp_f32_e32 v3, v3
	v_mov_b32_e32 v1, v2
	v_pk_mul_f32 v[158:159], v[0:1], v[156:157]
	v_mul_f32_e32 v2, v227, v3
	v_exp_f32_e32 v160, v2
	v_add_f32_e32 v2, v226, v11
	v_mul_f32_e32 v2, 0xbfb8aa3b, v2
	v_exp_f32_e32 v2, v2
	v_fma_f32 v3, -v160, v160, 1.0
	v_add_f32_e32 v2, 1.0, v2
	v_rcp_f32_e32 v2, v2
	v_pk_fma_f32 v[0:1], v[0:1], v[156:157], v[158:159] op_sel:[0,0,1] op_sel_hi:[1,1,0]
	v_mul_f32_e32 v5, v5, v160
	s_nop 0
	s_nop 1
	v_add_f32_e32 v6, v225, v28
	v_mul_f32_e32 v6, 0xbfb8aa3b, v6
	v_exp_f32_e32 v6, v6
	s_nop 1
	v_sqrt_f32_e32 v3, v3
	s_nop 0
	v_mul_f32_e32 v2, v2, v3
	v_add_f32_e32 v3, 1.0, v6
	v_rcp_f32_e32 v3, v3
	v_mov_b32_e32 v1, v2
	v_pk_mul_f32 v[162:163], v[0:1], v[160:161]
	v_mul_f32_e32 v2, v227, v3
	v_exp_f32_e32 v164, v2
	v_add_f32_e32 v2, v226, v12
	v_mul_f32_e32 v2, 0xbfb8aa3b, v2
	v_exp_f32_e32 v2, v2
	v_fma_f32 v3, -v164, v164, 1.0
	v_add_f32_e32 v2, 1.0, v2
	v_rcp_f32_e32 v2, v2
	v_pk_fma_f32 v[0:1], v[0:1], v[160:161], v[162:163] op_sel:[0,0,1] op_sel_hi:[1,1,0]
	v_mul_f32_e32 v5, v5, v164
	s_nop 0
	s_nop 1
	v_add_f32_e32 v6, v225, v29
	v_mul_f32_e32 v6, 0xbfb8aa3b, v6
	v_exp_f32_e32 v6, v6
	s_nop 1
	v_sqrt_f32_e32 v3, v3
	s_nop 0
	v_mul_f32_e32 v2, v2, v3
	v_add_f32_e32 v3, 1.0, v6
	v_rcp_f32_e32 v3, v3
	v_mov_b32_e32 v1, v2
	v_pk_mul_f32 v[166:167], v[0:1], v[164:165]
	v_mul_f32_e32 v2, v227, v3
	v_exp_f32_e32 v168, v2
	v_add_f32_e32 v2, v226, v13
	v_mul_f32_e32 v2, 0xbfb8aa3b, v2
	v_exp_f32_e32 v2, v2
	v_fma_f32 v3, -v168, v168, 1.0
	v_add_f32_e32 v2, 1.0, v2
	v_rcp_f32_e32 v2, v2
	v_pk_fma_f32 v[0:1], v[0:1], v[164:165], v[166:167] op_sel:[0,0,1] op_sel_hi:[1,1,0]
	v_mul_f32_e32 v5, v5, v168
	s_nop 0
	s_nop 1
	v_add_f32_e32 v6, v225, v30
	v_mul_f32_e32 v6, 0xbfb8aa3b, v6
	v_exp_f32_e32 v6, v6
	s_nop 1
	v_sqrt_f32_e32 v3, v3
	s_nop 0
	v_mul_f32_e32 v2, v2, v3
	v_add_f32_e32 v3, 1.0, v6
	v_rcp_f32_e32 v3, v3
	v_mov_b32_e32 v1, v2
	v_pk_mul_f32 v[170:171], v[0:1], v[168:169]
	v_mul_f32_e32 v2, v227, v3
	v_exp_f32_e32 v172, v2
	v_add_f32_e32 v2, v226, v14
	v_mul_f32_e32 v2, 0xbfb8aa3b, v2
	v_exp_f32_e32 v2, v2
	v_fma_f32 v3, -v172, v172, 1.0
	v_add_f32_e32 v2, 1.0, v2
	v_rcp_f32_e32 v2, v2
	v_pk_fma_f32 v[0:1], v[0:1], v[168:169], v[170:171] op_sel:[0,0,1] op_sel_hi:[1,1,0]
	v_mul_f32_e32 v5, v5, v172
	s_nop 0
	s_nop 1
	v_add_f32_e32 v6, v225, v31
	v_mul_f32_e32 v6, 0xbfb8aa3b, v6
	v_exp_f32_e32 v6, v6
	s_nop 1
	v_sqrt_f32_e32 v3, v3
	s_nop 0
	v_mul_f32_e32 v2, v2, v3
	v_add_f32_e32 v3, 1.0, v6
	v_rcp_f32_e32 v3, v3
	v_mov_b32_e32 v1, v2
	v_pk_mul_f32 v[174:175], v[0:1], v[172:173]
	v_mul_f32_e32 v2, v227, v3
	v_exp_f32_e32 v176, v2
	v_add_f32_e32 v2, v226, v15
	v_mul_f32_e32 v2, 0xbfb8aa3b, v2
	v_exp_f32_e32 v2, v2
	v_fma_f32 v3, -v176, v176, 1.0
	v_add_f32_e32 v2, 1.0, v2
	v_rcp_f32_e32 v2, v2
	v_pk_fma_f32 v[0:1], v[0:1], v[172:173], v[174:175] op_sel:[0,0,1] op_sel_hi:[1,1,0]
	s_nop 0
	s_nop 1
	s_add_i32 s8, s30, s10
	v_add3_u32 v117, s8, v215, v216
	v_sqrt_f32_e32 v3, v3
	s_nop 0
	v_mul_f32_e32 v2, v2, v3
	v_mov_b32_e32 v1, v2
	v_pk_mul_f32 v[178:179], v[0:1], v[176:177]
	s_mul_i32 s10, s23, 0x60000
	v_pk_fma_f32 v[0:1], v[0:1], v[176:177], v[178:179] op_sel_hi:[1,1,0]
	s_nop 0
	v_mul_f32_e32 v0, v5, v176
	ds_write_b64 v117, v[0:1] offset:17408
	v_add_co_u32_e32 v0, vcc, s60, v84
	s_waitcnt lgkmcnt(0)
	s_waitcnt vmcnt(15)
	ds_write_b128 v222, v[52:55] offset:33792
	s_waitcnt vmcnt(14)
	ds_write_b128 v222, v[60:63] offset:34880
	s_waitcnt vmcnt(13)
	ds_write_b128 v222, v[68:71] offset:35968
	s_waitcnt vmcnt(12)
	ds_write_b128 v222, v[76:79] offset:37056
	s_waitcnt vmcnt(11)
	ds_write_b128 v222, v[80:83] offset:38144
	s_waitcnt vmcnt(10)
	ds_write_b128 v222, v[88:91] offset:39232
	s_waitcnt vmcnt(9)
	ds_write_b128 v222, v[92:95] offset:40320
	s_waitcnt vmcnt(8)
	ds_write_b128 v222, v[96:99] offset:41408
	v_addc_co_u32_e32 v1, vcc, 0, v85, vcc
	v_add_co_u32_e32 v2, vcc, s61, v84
	s_nop 1
	v_addc_co_u32_e32 v3, vcc, 0, v85, vcc
	global_load_dwordx4 v[52:55], v[0:1], off
	global_load_dwordx4 v[60:63], v[2:3], off offset:2048
	v_add_co_u32_e32 v0, vcc, s62, v84
	s_nop 1
	v_addc_co_u32_e32 v1, vcc, 0, v85, vcc
	v_add_co_u32_e32 v2, vcc, s63, v84
	s_nop 1
	v_addc_co_u32_e32 v3, vcc, 0, v85, vcc
	global_load_dwordx4 v[68:71], v[0:1], off
	global_load_dwordx4 v[76:79], v[2:3], off offset:2048
	v_add_co_u32_e32 v0, vcc, s64, v84
	s_nop 1
	v_addc_co_u32_e32 v1, vcc, 0, v85, vcc
	v_add_co_u32_e32 v2, vcc, s65, v84
	s_nop 1
	v_addc_co_u32_e32 v3, vcc, 0, v85, vcc
	global_load_dwordx4 v[80:83], v[0:1], off
	global_load_dwordx4 v[88:91], v[2:3], off offset:2048
	v_add_co_u32_e32 v0, vcc, s66, v84
	s_nop 1
	v_addc_co_u32_e32 v1, vcc, 0, v85, vcc
	v_add_co_u32_e32 v2, vcc, s67, v84
	s_nop 1
	v_addc_co_u32_e32 v3, vcc, 0, v85, vcc
	global_load_dwordx4 v[92:95], v[0:1], off
	global_load_dwordx4 v[96:99], v[2:3], off offset:2048
	s_waitcnt lgkmcnt(0)
	ds_read_b128 v[0:3], v223 offset:33792
	ds_read_b128 v[4:7], v86
	ds_read_b128 v[180:183], v223 offset:33824
	ds_read_b128 v[184:187], v86 offset:32
	s_waitcnt lgkmcnt(2)
	v_mfma_f32_32x32x16_bf16 v[16:31], v[0:3], v[4:7], 0
	ds_read_b128 v[4:7], v86 offset:8704
	ds_read_b128 v[188:191], v86 offset:8736
	s_waitcnt lgkmcnt(1)
	v_mfma_f32_32x32x16_bf16 v[0:15], v[0:3], v[4:7], 0
	v_mfma_f32_32x32x16_bf16 v[16:31], v[180:183], v[184:187], v[16:31]
	s_waitcnt lgkmcnt(0)
	v_mfma_f32_32x32x16_bf16 v[0:15], v[180:183], v[188:191], v[0:15]
	ds_read_b128 v[180:183], v223 offset:33856
	ds_read_b128 v[184:187], v86 offset:64
	ds_read_b128 v[188:191], v223 offset:33888
	ds_read_b128 v[192:195], v86 offset:96
	s_waitcnt lgkmcnt(2)
	v_mfma_f32_32x32x16_bf16 v[16:31], v[180:183], v[184:187], v[16:31]
	ds_read_b128 v[184:187], v86 offset:8768
	ds_read_b128 v[196:199], v86 offset:8800
	s_waitcnt lgkmcnt(1)
	v_mfma_f32_32x32x16_bf16 v[0:15], v[180:183], v[184:187], v[0:15]
	v_mfma_f32_32x32x16_bf16 v[16:31], v[188:191], v[192:195], v[16:31]
	s_waitcnt lgkmcnt(0)
	v_mfma_f32_32x32x16_bf16 v[0:15], v[188:191], v[196:199], v[0:15]
	ds_read_b128 v[180:183], v223 offset:33920
	ds_read_b128 v[184:187], v86 offset:128
	ds_read_b128 v[188:191], v223 offset:33952
	ds_read_b128 v[192:195], v86 offset:160
	s_waitcnt lgkmcnt(2)
	v_mfma_f32_32x32x16_bf16 v[16:31], v[180:183], v[184:187], v[16:31]
	ds_read_b128 v[184:187], v86 offset:8832
	ds_read_b128 v[196:199], v86 offset:8864
	s_waitcnt lgkmcnt(1)
	v_mfma_f32_32x32x16_bf16 v[0:15], v[180:183], v[184:187], v[0:15]
	v_mfma_f32_32x32x16_bf16 v[16:31], v[188:191], v[192:195], v[16:31]
	s_waitcnt lgkmcnt(0)
	v_mfma_f32_32x32x16_bf16 v[0:15], v[188:191], v[196:199], v[0:15]
	ds_read_b128 v[180:183], v223 offset:33984
	ds_read_b128 v[184:187], v86 offset:192
	ds_read_b128 v[188:191], v223 offset:34016
	ds_read_b128 v[192:195], v86 offset:224
	s_waitcnt lgkmcnt(2)
	v_mfma_f32_32x32x16_bf16 v[16:31], v[180:183], v[184:187], v[16:31]
	ds_read_b128 v[184:187], v86 offset:8896
	ds_read_b128 v[196:199], v86 offset:8928
	s_waitcnt lgkmcnt(2)
	v_mfma_f32_32x32x16_bf16 v[16:31], v[188:191], v[192:195], v[16:31]
	s_waitcnt lgkmcnt(1)
	v_mfma_f32_32x32x16_bf16 v[0:15], v[180:183], v[184:187], v[0:15]
	s_nop 9
	v_add_f32_e32 v16, v225, v16
	v_mul_f32_e32 v16, 0xbfb8aa3b, v16
	v_exp_f32_e32 v16, v16
	v_add_f32_e32 v17, v225, v17
	v_mul_f32_e32 v17, 0xbfb8aa3b, v17
	v_add_f32_e32 v18, v225, v18
	v_add_f32_e32 v16, 1.0, v16
	v_rcp_f32_e32 v16, v16
	s_waitcnt lgkmcnt(0)
	v_mfma_f32_32x32x16_bf16 v[0:15], v[188:191], v[196:199], v[0:15]
	v_mul_f32_e32 v18, 0xbfb8aa3b, v18
	v_exp_f32_e32 v18, v18
	v_mul_f32_e32 v16, v227, v16
	v_exp_f32_e32 v16, v16
	v_add_f32_e32 v19, v225, v19
	v_add_f32_e32 v18, 1.0, v18
	v_rcp_f32_e32 v18, v18
	v_fma_f32 v84, -v16, v16, 1.0
	s_nop 1
	s_nop 1
	v_add_f32_e32 v0, v226, v0
	v_mul_f32_e32 v0, 0xbfb8aa3b, v0
	v_exp_f32_e32 v0, v0
	v_add_f32_e32 v1, v226, v1
	v_mul_f32_e32 v1, 0xbfb8aa3b, v1
	v_add_f32_e32 v0, 1.0, v0
	v_rcp_f32_e32 v0, v0
	v_exp_f32_e32 v1, v1
	v_exp_f32_e32 v86, v17
	v_add_f32_e32 v1, 1.0, v1
	v_rcp_f32_e32 v1, v1
	v_sqrt_f32_e32 v17, v84
	s_nop 0
	v_mul_f32_e32 v17, v0, v17
	v_add_f32_e32 v0, 1.0, v86
	v_rcp_f32_e32 v0, v0
	ds_read_u16 v84, v228 offset:33792
	ds_read_u16 v85, v228 offset:34064
	ds_read_u16 v86, v228 offset:34336
	ds_read_u16 v119, v228 offset:34608
	ds_read_u16 v120, v228 offset:34880
	ds_read_u16 v122, v228 offset:35152
	ds_read_u16 v125, v228 offset:35424
	ds_read_u16 v126, v228 offset:35696
	s_waitcnt lgkmcnt(7)
	v_lshlrev_b32_e32 v103, 16, v84
	v_pk_mul_f32 v[180:181], v[16:17], v[102:103]
	v_mul_f32_e32 v0, v227, v0
	v_exp_f32_e32 v0, v0
	v_add_f32_e32 v2, v226, v2
	v_mul_f32_e32 v2, 0xbfb8aa3b, v2
	v_exp_f32_e32 v2, v2
	v_fma_f32 v84, -v0, v0, 1.0
	v_add_f32_e32 v2, 1.0, v2
	v_mul_f32_e32 v19, 0xbfb8aa3b, v19
	v_rcp_f32_e32 v2, v2
	v_add_f32_e32 v20, v225, v20
	v_mul_f32_e32 v20, 0xbfb8aa3b, v20
	v_exp_f32_e32 v20, v20
	v_add_f32_e32 v21, v225, v21
	v_mul_f32_e32 v21, 0xbfb8aa3b, v21
	s_nop 1
	v_sqrt_f32_e32 v84, v84
	s_nop 0
	v_mul_f32_e32 v129, v1, v84
	s_waitcnt lgkmcnt(6)
	v_lshlrev_b32_e32 v1, 16, v85
	v_pk_fma_f32 v[84:85], v[16:17], v[102:103], v[180:181] op_sel:[0,0,1] op_sel_hi:[1,1,0]
	v_mul_f32_e32 v17, v227, v18
	v_exp_f32_e32 v18, v17
	v_mov_b32_e32 v85, v129
	v_pk_mul_f32 v[182:183], v[84:85], v[0:1]
	v_mul_f32_e32 v129, v16, v0
	v_fma_f32 v17, -v18, v18, 1.0
	v_pk_fma_f32 v[84:85], v[84:85], v[0:1], v[182:183] op_sel:[0,0,1] op_sel_hi:[1,1,0]
	s_nop 0
	s_nop 0
	s_nop 0
	s_nop 1
	v_exp_f32_e32 v130, v19
	s_waitcnt lgkmcnt(5)
	v_lshlrev_b32_e32 v19, 16, v86
	v_mul_f32_e32 v86, v129, v18
	v_sqrt_f32_e32 v17, v17
	s_nop 0
	v_mul_f32_e32 v2, v2, v17
	v_add_f32_e32 v17, 1.0, v130
	v_rcp_f32_e32 v17, v17
	v_mov_b32_e32 v85, v2
	v_pk_mul_f32 v[184:185], v[84:85], v[18:19]
	v_mul_f32_e32 v1, v227, v17
	v_exp_f32_e32 v2, v1
	v_add_f32_e32 v1, v226, v3
	v_mul_f32_e32 v1, 0xbfb8aa3b, v1
	v_exp_f32_e32 v1, v1
	v_fma_f32 v3, -v2, v2, 1.0
	v_add_f32_e32 v1, 1.0, v1
	v_rcp_f32_e32 v1, v1
	v_pk_fma_f32 v[84:85], v[84:85], v[18:19], v[184:185] op_sel:[0,0,1] op_sel_hi:[1,1,0]
	v_mul_f32_e32 v19, v86, v2
	s_nop 0
	s_nop 1
	s_nop 1
	v_sqrt_f32_e32 v3, v3
	s_nop 0
	v_add_f32_e32 v17, 1.0, v20
	v_rcp_f32_e32 v17, v17
	v_mul_f32_e32 v1, v1, v3
	v_mov_b32_e32 v85, v1
	s_waitcnt lgkmcnt(4)
	v_lshlrev_b32_e32 v3, 16, v119
	v_mul_f32_e32 v1, v227, v17
	v_exp_f32_e32 v20, v1
	v_add_f32_e32 v1, v226, v4
	v_mul_f32_e32 v1, 0xbfb8aa3b, v1
	v_exp_f32_e32 v1, v1
	v_fma_f32 v4, -v20, v20, 1.0
	v_add_f32_e32 v1, 1.0, v1
	v_rcp_f32_e32 v1, v1
	v_pk_mul_f32 v[186:187], v[84:85], v[2:3]
	v_pk_fma_f32 v[84:85], v[84:85], v[2:3], v[186:187] op_sel:[0,0,1] op_sel_hi:[1,1,0]
	s_nop 1
	v_exp_f32_e32 v86, v21
	s_waitcnt lgkmcnt(3)
	v_lshlrev_b32_e32 v21, 16, v120
	v_sqrt_f32_e32 v4, v4
	s_nop 0
	v_mul_f32_e32 v1, v1, v4
	v_add_f32_e32 v4, 1.0, v86
	v_rcp_f32_e32 v4, v4
	v_mov_b32_e32 v85, v1
	v_mul_f32_e32 v17, v19, v20
	v_pk_mul_f32 v[188:189], v[84:85], v[20:21]
	v_mul_f32_e32 v1, v227, v4
	v_exp_f32_e32 v4, v1
	v_add_f32_e32 v1, v226, v5
	v_mul_f32_e32 v1, 0xbfb8aa3b, v1
	v_exp_f32_e32 v1, v1
	v_fma_f32 v3, -v4, v4, 1.0
	v_add_f32_e32 v1, 1.0, v1
	v_rcp_f32_e32 v1, v1
	v_pk_fma_f32 v[84:85], v[84:85], v[20:21], v[188:189] op_sel:[0,0,1] op_sel_hi:[1,1,0]
	v_mul_f32_e32 v17, v17, v4
	s_nop 0
	s_nop 1
	v_add_f32_e32 v19, v225, v22
	v_mul_f32_e32 v19, 0xbfb8aa3b, v19
	v_exp_f32_e32 v19, v19
	s_nop 1
	v_sqrt_f32_e32 v3, v3
	s_nop 0
	v_mul_f32_e32 v1, v1, v3
	v_add_f32_e32 v3, 1.0, v19
	v_rcp_f32_e32 v3, v3
	v_mov_b32_e32 v85, v1
	s_waitcnt lgkmcnt(2)
	v_lshlrev_b32_e32 v5, 16, v122
	v_pk_mul_f32 v[190:191], v[84:85], v[4:5]
	v_mul_f32_e32 v1, v227, v3
	v_exp_f32_e32 v22, v1
	v_add_f32_e32 v1, v226, v6
	v_mul_f32_e32 v1, 0xbfb8aa3b, v1
	v_exp_f32_e32 v1, v1
	v_fma_f32 v3, -v22, v22, 1.0
	v_add_f32_e32 v1, 1.0, v1
	v_rcp_f32_e32 v1, v1
	v_pk_fma_f32 v[84:85], v[84:85], v[4:5], v[190:191] op_sel:[0,0,1] op_sel_hi:[1,1,0]
	v_mul_f32_e32 v17, v17, v22
	s_nop 0
	s_nop 1
	v_add_f32_e32 v19, v225, v23
	v_mul_f32_e32 v19, 0xbfb8aa3b, v19
	v_exp_f32_e32 v19, v19
	s_waitcnt lgkmcnt(1)
	v_lshlrev_b32_e32 v23, 16, v125
	v_sqrt_f32_e32 v3, v3
	s_nop 0
	v_mul_f32_e32 v1, v1, v3
	v_add_f32_e32 v3, 1.0, v19
	v_rcp_f32_e32 v3, v3
	v_mov_b32_e32 v85, v1
	v_pk_mul_f32 v[192:193], v[84:85], v[22:23]
	v_mul_f32_e32 v1, v227, v3
	v_exp_f32_e32 v6, v1
	v_add_f32_e32 v1, v226, v7
	v_mul_f32_e32 v1, 0xbfb8aa3b, v1
	v_exp_f32_e32 v1, v1
	v_fma_f32 v3, -v6, v6, 1.0
	v_add_f32_e32 v1, 1.0, v1
	v_rcp_f32_e32 v1, v1
	v_pk_fma_f32 v[84:85], v[84:85], v[22:23], v[192:193] op_sel:[0,0,1] op_sel_hi:[1,1,0]
	v_mul_f32_e32 v17, v17, v6
	s_nop 0
	s_nop 1
	v_add_f32_e32 v7, v225, v24
	v_mul_f32_e32 v7, 0xbfb8aa3b, v7
	v_exp_f32_e32 v19, v7
	s_waitcnt lgkmcnt(0)
	v_lshlrev_b32_e32 v7, 16, v126
	v_sqrt_f32_e32 v3, v3
	s_nop 0
	v_mul_f32_e32 v1, v1, v3
	v_add_f32_e32 v3, 1.0, v19
	v_rcp_f32_e32 v3, v3
	v_mov_b32_e32 v85, v1
	v_pk_mul_f32 v[194:195], v[84:85], v[6:7]
	v_mul_f32_e32 v1, v227, v3
	v_exp_f32_e32 v24, v1
	v_add_f32_e32 v1, v226, v8
	v_mul_f32_e32 v1, 0xbfb8aa3b, v1
	v_exp_f32_e32 v1, v1
	v_fma_f32 v3, -v24, v24, 1.0
	v_add_f32_e32 v1, 1.0, v1
	v_rcp_f32_e32 v1, v1
	v_pk_fma_f32 v[84:85], v[84:85], v[6:7], v[194:195] op_sel:[0,0,1] op_sel_hi:[1,1,0]
	v_mul_f32_e32 v7, v17, v24
	s_nop 0
	s_nop 1
	s_nop 1
	v_sqrt_f32_e32 v3, v3
	s_nop 0
	v_mul_f32_e32 v1, v1, v3
	v_add_f32_e32 v3, v225, v25
	v_mul_f32_e32 v3, 0xbfb8aa3b, v3
	v_exp_f32_e32 v3, v3
	v_mov_b32_e32 v85, v1
	ds_read_u16 v5, v228 offset:35968
	ds_read_u16 v19, v228 offset:36240
	ds_read_u16 v21, v228 offset:36512
	ds_read_u16 v23, v228 offset:36784
	ds_read_u16 v86, v228 offset:37056
	ds_read_u16 v103, v228 offset:37328
	ds_read_u16 v119, v228 offset:37600
	ds_read_u16 v120, v228 offset:37872
	s_waitcnt lgkmcnt(7)
	v_lshlrev_b32_e32 v25, 16, v5
	v_add_f32_e32 v3, 1.0, v3
	v_rcp_f32_e32 v3, v3
	v_pk_mul_f32 v[196:197], v[84:85], v[24:25]
	v_mul_f32_e32 v1, v227, v3
	v_exp_f32_e32 v8, v1
	v_add_f32_e32 v1, v226, v9
	v_mul_f32_e32 v1, 0xbfb8aa3b, v1
	v_exp_f32_e32 v1, v1
	v_fma_f32 v3, -v8, v8, 1.0
	v_add_f32_e32 v1, 1.0, v1
	v_rcp_f32_e32 v1, v1
	v_pk_fma_f32 v[84:85], v[84:85], v[24:25], v[196:197] op_sel:[0,0,1] op_sel_hi:[1,1,0]
	v_mul_f32_e32 v7, v7, v8
	s_nop 0
	s_nop 1
	v_add_f32_e32 v9, v225, v26
	v_mul_f32_e32 v9, 0xbfb8aa3b, v9
	v_exp_f32_e32 v17, v9
	s_waitcnt lgkmcnt(6)
	v_lshlrev_b32_e32 v9, 16, v19
	v_sqrt_f32_e32 v3, v3
	s_nop 0
	v_mul_f32_e32 v1, v1, v3
	v_add_f32_e32 v3, 1.0, v17
	v_rcp_f32_e32 v3, v3
	v_mov_b32_e32 v85, v1
	v_pk_mul_f32 v[198:199], v[84:85], v[8:9]
	v_mul_f32_e32 v1, v227, v3
	v_exp_f32_e32 v26, v1
	v_add_f32_e32 v1, v226, v10
	v_mul_f32_e32 v1, 0xbfb8aa3b, v1
	v_exp_f32_e32 v1, v1
	v_fma_f32 v3, -v26, v26, 1.0
	v_add_f32_e32 v1, 1.0, v1
	v_rcp_f32_e32 v1, v1
	v_pk_fma_f32 v[84:85], v[84:85], v[8:9], v[198:199] op_sel:[0,0,1] op_sel_hi:[1,1,0]
	v_mul_f32_e32 v7, v7, v26
	s_nop 0
	s_nop 1
	v_add_f32_e32 v10, v225, v27
	v_mul_f32_e32 v10, 0xbfb8aa3b, v10
	v_exp_f32_e32 v10, v10
	s_waitcnt lgkmcnt(5)
	v_lshlrev_b32_e32 v27, 16, v21
	v_sqrt_f32_e32 v3, v3
	s_nop 0
	v_mul_f32_e32 v1, v1, v3
	v_add_f32_e32 v3, 1.0, v10
	v_rcp_f32_e32 v3, v3
	v_mov_b32_e32 v85, v1
	v_pk_mul_f32 v[200:201], v[84:85], v[26:27]
	v_mul_f32_e32 v1, v227, v3
	v_exp_f32_e32 v10, v1
	v_add_f32_e32 v1, v226, v11
	v_mul_f32_e32 v1, 0xbfb8aa3b, v1
	v_exp_f32_e32 v1, v1
	v_fma_f32 v3, -v10, v10, 1.0
	v_add_f32_e32 v1, 1.0, v1
	v_rcp_f32_e32 v1, v1
	v_pk_fma_f32 v[84:85], v[84:85], v[26:27], v[200:201] op_sel:[0,0,1] op_sel_hi:[1,1,0]
	v_mul_f32_e32 v7, v7, v10
	s_nop 0
	s_nop 1
	v_add_f32_e32 v9, v225, v28
	v_mul_f32_e32 v9, 0xbfb8aa3b, v9
	v_exp_f32_e32 v9, v9
	s_waitcnt lgkmcnt(4)
	v_lshlrev_b32_e32 v11, 16, v23
	v_sqrt_f32_e32 v3, v3
	s_nop 0
	v_mul_f32_e32 v1, v1, v3
	v_add_f32_e32 v3, 1.0, v9
	v_rcp_f32_e32 v3, v3
	v_mov_b32_e32 v85, v1
	v_pk_mul_f32 v[202:203], v[84:85], v[10:11]
	v_mul_f32_e32 v1, v227, v3
	v_exp_f32_e32 v28, v1
	v_add_f32_e32 v1, v226, v12
	v_mul_f32_e32 v1, 0xbfb8aa3b, v1
	v_exp_f32_e32 v1, v1
	v_fma_f32 v3, -v28, v28, 1.0
	v_add_f32_e32 v1, 1.0, v1
	v_rcp_f32_e32 v1, v1
	v_pk_fma_f32 v[84:85], v[84:85], v[10:11], v[202:203] op_sel:[0,0,1] op_sel_hi:[1,1,0]
	v_mul_f32_e32 v7, v7, v28
	s_nop 0
	s_nop 1
	v_add_f32_e32 v9, v225, v29
	v_mul_f32_e32 v9, 0xbfb8aa3b, v9
	v_exp_f32_e32 v9, v9
	s_waitcnt lgkmcnt(3)
	v_lshlrev_b32_e32 v29, 16, v86
	v_sqrt_f32_e32 v3, v3
	s_nop 0
	v_mul_f32_e32 v1, v1, v3
	v_add_f32_e32 v3, 1.0, v9
	v_rcp_f32_e32 v3, v3
	v_mov_b32_e32 v85, v1
	v_pk_mul_f32 v[204:205], v[84:85], v[28:29]
	v_mul_f32_e32 v1, v227, v3
	v_exp_f32_e32 v12, v1
	v_add_f32_e32 v1, v226, v13
	v_mul_f32_e32 v1, 0xbfb8aa3b, v1
	v_exp_f32_e32 v1, v1
	v_fma_f32 v3, -v12, v12, 1.0
	v_add_f32_e32 v1, 1.0, v1
	v_rcp_f32_e32 v1, v1
	v_pk_fma_f32 v[84:85], v[84:85], v[28:29], v[204:205] op_sel:[0,0,1] op_sel_hi:[1,1,0]
	s_waitcnt lgkmcnt(2)
	v_lshlrev_b32_e32 v13, 16, v103
	v_mul_f32_e32 v7, v7, v12
	s_nop 0
	s_nop 1
	v_add_f32_e32 v9, v225, v30
	v_mul_f32_e32 v9, 0xbfb8aa3b, v9
	v_exp_f32_e32 v9, v9
	s_nop 1
	v_sqrt_f32_e32 v3, v3
	s_nop 0
	v_mul_f32_e32 v1, v1, v3
	v_add_f32_e32 v3, 1.0, v9
	v_rcp_f32_e32 v3, v3
	v_mov_b32_e32 v85, v1
	v_pk_mul_f32 v[206:207], v[84:85], v[12:13]
	v_mul_f32_e32 v1, v227, v3
	v_exp_f32_e32 v30, v1
	v_add_f32_e32 v1, v226, v14
	v_mul_f32_e32 v1, 0xbfb8aa3b, v1
	v_exp_f32_e32 v1, v1
	v_fma_f32 v3, -v30, v30, 1.0
	v_add_f32_e32 v1, 1.0, v1
	v_rcp_f32_e32 v1, v1
	v_pk_fma_f32 v[84:85], v[84:85], v[12:13], v[206:207] op_sel:[0,0,1] op_sel_hi:[1,1,0]
	v_mul_f32_e32 v7, v7, v30
	s_nop 0
	s_nop 1
	v_add_f32_e32 v9, v225, v31
	v_mul_f32_e32 v9, 0xbfb8aa3b, v9
	v_exp_f32_e32 v9, v9
	s_waitcnt lgkmcnt(1)
	v_lshlrev_b32_e32 v31, 16, v119
	v_sqrt_f32_e32 v3, v3
	s_nop 0
	v_mul_f32_e32 v1, v1, v3
	v_add_f32_e32 v3, 1.0, v9
	v_rcp_f32_e32 v3, v3
	v_mov_b32_e32 v85, v1
	v_pk_mul_f32 v[208:209], v[84:85], v[30:31]
	v_mul_f32_e32 v1, v227, v3
	v_exp_f32_e32 v14, v1
	v_add_f32_e32 v1, v226, v15
	v_mul_f32_e32 v1, 0xbfb8aa3b, v1
	v_exp_f32_e32 v1, v1
	v_fma_f32 v3, -v14, v14, 1.0
	v_add_f32_e32 v1, 1.0, v1
	v_rcp_f32_e32 v1, v1
	v_pk_fma_f32 v[84:85], v[84:85], v[30:31], v[208:209] op_sel:[0,0,1] op_sel_hi:[1,1,0]
	s_waitcnt lgkmcnt(0)
	v_lshlrev_b32_e32 v15, 16, v120
	s_nop 0
	s_nop 1
	s_ashr_i32 s9, s10, 31
	s_mov_b32 s8, s10
	v_sqrt_f32_e32 v3, v3
	s_nop 0
	v_mul_f32_e32 v1, v1, v3
	v_mov_b32_e32 v85, v1
	v_lshl_add_u64 v[230:231], s[8:9], 1, v[112:113]
	v_pk_mul_f32 v[210:211], v[84:85], v[14:15]
	v_add_co_u32_e32 v232, vcc, s52, v230
	v_pk_fma_f32 v[84:85], v[84:85], v[14:15], v[210:211] op_sel_hi:[1,1,0]
	s_nop 0
	v_addc_co_u32_e32 v233, vcc, 0, v231, vcc
	v_mul_f32_e32 v84, v7, v14
	v_add_co_u32_e32 v234, vcc, s51, v230
	ds_write_b64 v117, v[84:85] offset:17920
	v_lshl_add_u64 v[84:85], s[10:11], 1, v[112:113]
	v_addc_co_u32_e32 v235, vcc, 0, v231, vcc
	s_waitcnt lgkmcnt(0)
	s_waitcnt lgkmcnt(0)
	s_barrier
	global_load_ushort v146, v[84:85], off
	global_load_ushort v145, v[230:231], off offset:1536
	global_load_ushort v141, v[230:231], off offset:3072
	global_load_ushort v138, v[232:233], off offset:512
	global_load_ushort v137, v[232:233], off offset:2048
	global_load_ushort v134, v[232:233], off offset:3584
	global_load_ushort v133, v[234:235], off offset:1024
	global_load_ushort v125, v[234:235], off offset:2560
	v_add_co_u32_e32 v84, vcc, s53, v230
	s_mov_b32 s10, 0
	s_nop 0
	v_addc_co_u32_e32 v85, vcc, 0, v231, vcc
	v_add_co_u32_e32 v232, vcc, s54, v230
	s_nop 1
	v_addc_co_u32_e32 v233, vcc, 0, v231, vcc
	v_add_co_u32_e32 v234, vcc, s68, v230
	s_nop 1
	v_addc_co_u32_e32 v235, vcc, 0, v231, vcc
	global_load_ushort v130, v[84:85], off
	global_load_ushort v129, v[84:85], off offset:1536
	global_load_ushort v126, v[84:85], off offset:3072
	global_load_ushort v122, v[232:233], off offset:512
	global_load_ushort v120, v[232:233], off offset:2048
	global_load_ushort v117, v[232:233], off offset:3584
	global_load_ushort v103, v[234:235], off offset:1024
	global_load_ushort v29, v[234:235], off offset:2560
	v_add_co_u32_e32 v84, vcc, s60, v230
	s_nop 1
	v_addc_co_u32_e32 v85, vcc, 0, v231, vcc
	v_add_co_u32_e32 v232, vcc, s61, v230
	s_nop 1
	v_addc_co_u32_e32 v233, vcc, 0, v231, vcc
	v_add_co_u32_e32 v234, vcc, 0xe000, v230
	s_nop 1
	v_addc_co_u32_e32 v235, vcc, 0, v231, vcc
	global_load_ushort v119, v[84:85], off
	global_load_ushort v31, v[84:85], off offset:1536
	global_load_ushort v27, v[84:85], off offset:3072
	global_load_ushort v25, v[232:233], off offset:512
	global_load_ushort v23, v[232:233], off offset:2048
	global_load_ushort v19, v[232:233], off offset:3584
	global_load_ushort v17, v[234:235], off offset:1024
	global_load_ushort v13, v[234:235], off offset:2560
	v_add_co_u32_e32 v84, vcc, s62, v230
	s_nop 1
	v_addc_co_u32_e32 v85, vcc, 0, v231, vcc
	v_add_co_u32_e32 v232, vcc, 0x10000, v230
	s_nop 1
	v_addc_co_u32_e32 v233, vcc, 0, v231, vcc
	v_add_co_u32_e32 v230, vcc, 0x11000, v230
	s_nop 1
	v_addc_co_u32_e32 v231, vcc, 0, v231, vcc
	global_load_ushort v21, v[84:85], off
	global_load_ushort v15, v[84:85], off offset:1536
	global_load_ushort v11, v[84:85], off offset:3072
	global_load_ushort v9, v[232:233], off offset:512
	global_load_ushort v7, v[232:233], off offset:2048
	global_load_ushort v5, v[232:233], off offset:3584
	global_load_ushort v3, v[230:231], off offset:1024
	global_load_ushort v1, v[230:231], off offset:2560
	v_cndmask_b32_e64 v84, 0, 1, s[20:21]
	v_lshl_add_u32 v149, v84, 13, v218

	.amdhsa_kernel _Z8fwd_mega4Args
		.amdhsa_group_segment_fixed_size 0
		.amdhsa_private_segment_fixed_size 0
		.amdhsa_kernarg_size 472
		.amdhsa_user_sgpr_count 2
		.amdhsa_user_sgpr_dispatch_ptr 0
		.amdhsa_user_sgpr_queue_ptr 0
		.amdhsa_user_sgpr_kernarg_segment_ptr 1
		.amdhsa_user_sgpr_dispatch_id 0
		.amdhsa_user_sgpr_kernarg_preload_length 0
		.amdhsa_user_sgpr_kernarg_preload_offset 0
		.amdhsa_user_sgpr_private_segment_size 0
		.amdhsa_uses_dynamic_stack 0
		.amdhsa_enable_private_segment 0
		.amdhsa_system_sgpr_workgroup_id_x 1
		.amdhsa_system_sgpr_workgroup_id_y 0
		.amdhsa_system_sgpr_workgroup_id_z 0
		.amdhsa_system_sgpr_workgroup_info 0
		.amdhsa_system_vgpr_workitem_id 2
		.amdhsa_next_free_vgpr 256
		.amdhsa_next_free_sgpr 102
		.amdhsa_accum_offset 256
		.amdhsa_reserve_vcc 1
		.amdhsa_float_round_mode_32 0
		.amdhsa_float_round_mode_16_64 0
		.amdhsa_float_denorm_mode_32 3
		.amdhsa_float_denorm_mode_16_64 3
		.amdhsa_dx10_clamp 1
		.amdhsa_ieee_mode 1
		.amdhsa_fp16_overflow 0
		.amdhsa_tg_split 0
		.amdhsa_exception_fp_ieee_invalid_op 0
		.amdhsa_exception_fp_denorm_src 0
		.amdhsa_exception_fp_ieee_div_zero 0
		.amdhsa_exception_fp_ieee_overflow 0
		.amdhsa_exception_fp_ieee_underflow 0
		.amdhsa_exception_fp_ieee_inexact 0
		.amdhsa_exception_int_div_zero 0
	.end_amdhsa_kernel

amdhsa.kernels:
  - .agpr_count:     0
    .args:
      - .offset:         0
        .size:           216
        .value_kind:     by_value
      - .offset:         216
        .size:           4
        .value_kind:     hidden_block_count_x
      - .offset:         220
        .size:           4
        .value_kind:     hidden_block_count_y
      - .offset:         224
        .size:           4
        .value_kind:     hidden_block_count_z
      - .offset:         228
        .size:           2
        .value_kind:     hidden_group_size_x
      - .offset:         230
        .size:           2
        .value_kind:     hidden_group_size_y
      - .offset:         232
        .size:           2
        .value_kind:     hidden_group_size_z
      - .offset:         234
        .size:           2
        .value_kind:     hidden_remainder_x
      - .offset:         236
        .size:           2
        .value_kind:     hidden_remainder_y
      - .offset:         238
        .size:           2
        .value_kind:     hidden_remainder_z
      - .offset:         256
        .size:           8
        .value_kind:     hidden_global_offset_x
      - .offset:         264
        .size:           8
        .value_kind:     hidden_global_offset_y
      - .offset:         272
        .size:           8
        .value_kind:     hidden_global_offset_z
      - .offset:         280
        .size:           2
        .value_kind:     hidden_grid_dims
      - .offset:         304
        .size:           8
        .value_kind:     hidden_multigrid_sync_arg
      - .offset:         336
        .size:           4
        .value_kind:     hidden_dynamic_lds_size
    .group_segment_fixed_size: 0
    .kernarg_segment_align: 8
    .kernarg_segment_size: 472
    .language:       OpenCL C
    .language_version:
      - 2
      - 0
    .max_flat_workgroup_size: 512
    .name:           _Z8fwd_mega4Args
    .private_segment_fixed_size: 0
    .sgpr_count:     108
    .sgpr_spill_count: 8
    .symbol:         _Z8fwd_mega4Args.kd
    .uniform_work_group_size: 1
    .uses_dynamic_stack: false
    .vgpr_count:     256
    .vgpr_spill_count: 0
    .wavefront_size: 64
